# leading half issues its epilogue loads before the epilogue-alignment barrier (barrier moved behind the load issue) in 7 GEMM phases
# speedup vs baseline: 1.0189x; 1.0033x over previous
.LBB0_323:
	ds_read_b128 v[96:99], v209
	ds_read_b128 v[100:103], v209 offset:1024
	ds_read_b128 v[120:123], v209 offset:2048
	ds_read_b128 v[124:127], v209 offset:3072
	ds_read_b128 v[144:147], v210
	ds_read_b128 v[148:151], v210 offset:1024
	ds_read_b128 v[152:155], v210 offset:2048
	ds_read_b128 v[156:159], v210 offset:3072
	s_add_u32 s8, s6, 0xfffc0080
	s_addc_u32 s9, s7, -1
	s_cmp_eq_u32 s78, 12
	s_cselect_b32 s51, s18, s9
	s_cselect_b32 s50, s43, s8
	s_cselect_b32 s9, s45, s57
	s_cselect_b32 s8, s55, s56
	v_lshl_add_u64 v[206:207], s[6:7], 0, v[170:171]
	s_add_i32 m0, s17, 0xc000
	ds_read_b128 v[178:181], v211
	ds_read_b128 v[182:185], v211 offset:1024
	ds_read_b128 v[186:189], v211 offset:2048
	ds_read_b128 v[190:193], v211 offset:3072
	ds_read_b128 v[194:197], v211 offset:4096
	ds_read_b128 v[198:201], v211 offset:5120
	ds_read_b128 v[202:205], v211 offset:6144
	ds_read_b128 v[218:221], v211 offset:7168
	global_load_lds_dwordx4 v[206:207], off
	v_lshl_add_u64 v[206:207], s[6:7], 0, v[172:173]
	s_add_i32 m0, s17, 0xe000
	s_nop 0
	global_load_lds_dwordx4 v[206:207], off
	s_waitcnt vmcnt(8)
	s_waitcnt lgkmcnt(0)
	s_barrier
	s_setprio 1
	s_waitcnt lgkmcnt(0)
	v_mfma_f32_16x16x32_bf16 v[140:143], v[96:99], v[178:181], v[140:143]
	v_mfma_f32_16x16x32_bf16 v[136:139], v[120:123], v[178:181], v[136:139]
	v_mfma_f32_16x16x32_bf16 v[116:119], v[96:99], v[186:189], v[116:119]
	v_mfma_f32_16x16x32_bf16 v[112:115], v[120:123], v[186:189], v[112:115]
	v_mfma_f32_16x16x32_bf16 v[92:95], v[96:99], v[194:197], v[92:95]
	v_mfma_f32_16x16x32_bf16 v[88:91], v[120:123], v[194:197], v[88:91]
	v_mfma_f32_16x16x32_bf16 v[76:79], v[96:99], v[202:205], v[76:79]
	v_mfma_f32_16x16x32_bf16 v[72:75], v[120:123], v[202:205], v[72:75]
	v_mfma_f32_16x16x32_bf16 v[140:143], v[100:103], v[182:185], v[140:143]
	v_mfma_f32_16x16x32_bf16 v[136:139], v[124:127], v[182:185], v[136:139]
	v_mfma_f32_16x16x32_bf16 v[116:119], v[100:103], v[190:193], v[116:119]
	v_mfma_f32_16x16x32_bf16 v[112:115], v[124:127], v[190:193], v[112:115]
	v_mfma_f32_16x16x32_bf16 v[92:95], v[100:103], v[198:201], v[92:95]
	v_mfma_f32_16x16x32_bf16 v[88:91], v[124:127], v[198:201], v[88:91]
	v_mfma_f32_16x16x32_bf16 v[76:79], v[100:103], v[218:221], v[76:79]
	v_mfma_f32_16x16x32_bf16 v[72:75], v[124:127], v[218:221], v[72:75]
	s_setprio 0
	s_setprio 1
	v_mfma_f32_16x16x32_bf16 v[132:135], v[144:147], v[178:181], v[132:135]
	v_mfma_f32_16x16x32_bf16 v[128:131], v[152:155], v[178:181], v[128:131]
	v_mfma_f32_16x16x32_bf16 v[108:111], v[144:147], v[186:189], v[108:111]
	v_mfma_f32_16x16x32_bf16 v[104:107], v[152:155], v[186:189], v[104:107]
	v_mfma_f32_16x16x32_bf16 v[84:87], v[144:147], v[194:197], v[84:87]
	v_mfma_f32_16x16x32_bf16 v[80:83], v[152:155], v[194:197], v[80:83]
	v_mfma_f32_16x16x32_bf16 v[68:71], v[144:147], v[202:205], v[68:71]
	v_mfma_f32_16x16x32_bf16 v[64:67], v[152:155], v[202:205], v[64:67]
	v_mfma_f32_16x16x32_bf16 v[132:135], v[148:151], v[182:185], v[132:135]
	v_mfma_f32_16x16x32_bf16 v[128:131], v[156:159], v[182:185], v[128:131]
	v_mfma_f32_16x16x32_bf16 v[108:111], v[148:151], v[190:193], v[108:111]
	v_mfma_f32_16x16x32_bf16 v[104:107], v[156:159], v[190:193], v[104:107]
	s_setprio 2
	s_barrier
	v_mfma_f32_16x16x32_bf16 v[84:87], v[148:151], v[198:201], v[84:87]
	v_mfma_f32_16x16x32_bf16 v[80:83], v[156:159], v[198:201], v[80:83]
	v_mfma_f32_16x16x32_bf16 v[68:71], v[148:151], v[218:221], v[68:71]
	v_mfma_f32_16x16x32_bf16 v[64:67], v[156:159], v[218:221], v[64:67]
	s_setprio 0
	s_add_i32 s79, s73, s61
	v_lshl_add_u64 v[206:207], s[8:9], 0, v[162:163]
	s_mov_b32 m0, s79
	ds_read_b128 v[178:181], v211 offset:16384
	ds_read_b128 v[182:185], v211 offset:17408
	ds_read_b128 v[186:189], v211 offset:18432
	ds_read_b128 v[190:193], v211 offset:19456
	ds_read_b128 v[194:197], v211 offset:20480
	ds_read_b128 v[198:201], v211 offset:21504
	ds_read_b128 v[202:205], v211 offset:22528
	ds_read_b128 v[218:221], v211 offset:23552
	global_load_lds_dwordx4 v[206:207], off
	s_add_i32 m0, s79, 0x2000
	s_add_u32 s80, s8, 0x40000
	v_lshl_add_u64 v[222:223], s[8:9], 0, v[166:167]
	s_addc_u32 s81, s9, 0
	s_add_i32 s79, s74, s61
	global_load_lds_dwordx4 v[222:223], off
	v_lshl_add_u64 v[224:225], s[80:81], 0, v[162:163]
	s_mov_b32 m0, s79
	v_lshl_add_u64 v[226:227], s[50:51], 0, v[164:165]
	global_load_lds_dwordx4 v[224:225], off
	v_lshl_add_u64 v[224:225], s[80:81], 0, v[166:167]
	s_add_i32 m0, s79, 0x2000
	s_nop 0
	global_load_lds_dwordx4 v[224:225], off
	v_lshl_add_u64 v[224:225], s[50:51], 0, v[160:161]
	s_mov_b32 m0, s17
	s_nop 0
	global_load_lds_dwordx4 v[224:225], off
	s_mov_b32 m0, s62
	s_nop 0
	global_load_lds_dwordx4 v[226:227], off
	s_waitcnt vmcnt(8)
	s_waitcnt lgkmcnt(0)
	s_barrier
	s_setprio 1
	s_waitcnt lgkmcnt(0)
	v_mfma_f32_16x16x32_bf16 v[60:63], v[96:99], v[178:181], v[60:63]
	v_mfma_f32_16x16x32_bf16 v[56:59], v[120:123], v[178:181], v[56:59]
	v_mfma_f32_16x16x32_bf16 v[44:47], v[96:99], v[186:189], v[44:47]
	v_mfma_f32_16x16x32_bf16 v[40:43], v[120:123], v[186:189], v[40:43]
	v_mfma_f32_16x16x32_bf16 v[28:31], v[96:99], v[194:197], v[28:31]
	v_mfma_f32_16x16x32_bf16 v[24:27], v[120:123], v[194:197], v[24:27]
	v_mfma_f32_16x16x32_bf16 v[12:15], v[96:99], v[202:205], v[12:15]
	v_mfma_f32_16x16x32_bf16 v[8:11], v[120:123], v[202:205], v[8:11]
	v_mfma_f32_16x16x32_bf16 v[60:63], v[100:103], v[182:185], v[60:63]
	v_mfma_f32_16x16x32_bf16 v[56:59], v[124:127], v[182:185], v[56:59]
	v_mfma_f32_16x16x32_bf16 v[44:47], v[100:103], v[190:193], v[44:47]
	v_mfma_f32_16x16x32_bf16 v[40:43], v[124:127], v[190:193], v[40:43]
	v_mfma_f32_16x16x32_bf16 v[28:31], v[100:103], v[198:201], v[28:31]
	v_mfma_f32_16x16x32_bf16 v[24:27], v[124:127], v[198:201], v[24:27]
	v_mfma_f32_16x16x32_bf16 v[12:15], v[100:103], v[218:221], v[12:15]
	v_mfma_f32_16x16x32_bf16 v[8:11], v[124:127], v[218:221], v[8:11]
	s_setprio 0
	s_setprio 1
	v_mfma_f32_16x16x32_bf16 v[52:55], v[144:147], v[178:181], v[52:55]
	v_mfma_f32_16x16x32_bf16 v[48:51], v[152:155], v[178:181], v[48:51]
	v_mfma_f32_16x16x32_bf16 v[36:39], v[144:147], v[186:189], v[36:39]
	v_mfma_f32_16x16x32_bf16 v[32:35], v[152:155], v[186:189], v[32:35]
	v_mfma_f32_16x16x32_bf16 v[20:23], v[144:147], v[194:197], v[20:23]
	v_mfma_f32_16x16x32_bf16 v[16:19], v[152:155], v[194:197], v[16:19]
	v_mfma_f32_16x16x32_bf16 v[4:7], v[144:147], v[202:205], v[4:7]
	v_mfma_f32_16x16x32_bf16 v[0:3], v[152:155], v[202:205], v[0:3]
	v_mfma_f32_16x16x32_bf16 v[52:55], v[148:151], v[182:185], v[52:55]
	v_mfma_f32_16x16x32_bf16 v[48:51], v[156:159], v[182:185], v[48:51]
	v_mfma_f32_16x16x32_bf16 v[36:39], v[148:151], v[190:193], v[36:39]
	v_mfma_f32_16x16x32_bf16 v[32:35], v[156:159], v[190:193], v[32:35]
	s_setprio 2
	s_barrier
	v_mfma_f32_16x16x32_bf16 v[20:23], v[148:151], v[198:201], v[20:23]
	v_mfma_f32_16x16x32_bf16 v[16:19], v[156:159], v[198:201], v[16:19]
	v_mfma_f32_16x16x32_bf16 v[4:7], v[148:151], v[218:221], v[4:7]
	v_mfma_f32_16x16x32_bf16 v[0:3], v[156:159], v[218:221], v[0:3]
	s_setprio 0
	s_add_i32 s79, 0, 0x18000
	s_add_i32 s80, 0, 0x1c000
	v_add_u32_e32 v124, s79, v208
	v_add_u32_e32 v156, s80, v208
	ds_read_b128 v[96:99], v124
	ds_read_b128 v[100:103], v124 offset:1024
	ds_read_b128 v[120:123], v124 offset:2048
	ds_read_b128 v[124:127], v124 offset:3072
	ds_read_b128 v[144:147], v156
	ds_read_b128 v[148:151], v156 offset:1024
	ds_read_b128 v[152:155], v156 offset:2048
	ds_read_b128 v[156:159], v156 offset:3072
	s_add_u32 s50, s50, 0x40000
	s_addc_u32 s51, s51, 0
	s_mov_b32 m0, s63
	v_lshl_add_u64 v[228:229], s[50:51], 0, v[160:161]
	ds_read_b128 v[178:181], v211 offset:32768
	ds_read_b128 v[182:185], v211 offset:33792
	ds_read_b128 v[186:189], v211 offset:34816
	ds_read_b128 v[190:193], v211 offset:35840
	ds_read_b128 v[194:197], v211 offset:36864
	ds_read_b128 v[198:201], v211 offset:37888
	ds_read_b128 v[202:205], v211 offset:38912
	ds_read_b128 v[218:221], v211 offset:39936
	global_load_lds_dwordx4 v[228:229], off
	v_lshl_add_u64 v[228:229], s[50:51], 0, v[164:165]
	s_mov_b32 m0, s64
	s_nop 0
	global_load_lds_dwordx4 v[228:229], off
	s_waitcnt vmcnt(8)
	s_waitcnt lgkmcnt(0)
	s_barrier
	s_setprio 1
	s_waitcnt lgkmcnt(0)
	v_mfma_f32_16x16x32_bf16 v[140:143], v[96:99], v[178:181], v[140:143]
	v_mfma_f32_16x16x32_bf16 v[136:139], v[120:123], v[178:181], v[136:139]
	v_mfma_f32_16x16x32_bf16 v[116:119], v[96:99], v[186:189], v[116:119]
	v_mfma_f32_16x16x32_bf16 v[112:115], v[120:123], v[186:189], v[112:115]
	v_mfma_f32_16x16x32_bf16 v[92:95], v[96:99], v[194:197], v[92:95]
	v_mfma_f32_16x16x32_bf16 v[88:91], v[120:123], v[194:197], v[88:91]
	v_mfma_f32_16x16x32_bf16 v[76:79], v[96:99], v[202:205], v[76:79]
	v_mfma_f32_16x16x32_bf16 v[72:75], v[120:123], v[202:205], v[72:75]
	v_mfma_f32_16x16x32_bf16 v[140:143], v[100:103], v[182:185], v[140:143]
	v_mfma_f32_16x16x32_bf16 v[136:139], v[124:127], v[182:185], v[136:139]
	v_mfma_f32_16x16x32_bf16 v[116:119], v[100:103], v[190:193], v[116:119]
	v_mfma_f32_16x16x32_bf16 v[112:115], v[124:127], v[190:193], v[112:115]
	v_mfma_f32_16x16x32_bf16 v[92:95], v[100:103], v[198:201], v[92:95]
	v_mfma_f32_16x16x32_bf16 v[88:91], v[124:127], v[198:201], v[88:91]
	v_mfma_f32_16x16x32_bf16 v[76:79], v[100:103], v[218:221], v[76:79]
	v_mfma_f32_16x16x32_bf16 v[72:75], v[124:127], v[218:221], v[72:75]
	s_setprio 0
	s_setprio 1
	v_mfma_f32_16x16x32_bf16 v[132:135], v[144:147], v[178:181], v[132:135]
	v_mfma_f32_16x16x32_bf16 v[128:131], v[152:155], v[178:181], v[128:131]
	v_mfma_f32_16x16x32_bf16 v[108:111], v[144:147], v[186:189], v[108:111]
	v_mfma_f32_16x16x32_bf16 v[104:107], v[152:155], v[186:189], v[104:107]
	v_mfma_f32_16x16x32_bf16 v[84:87], v[144:147], v[194:197], v[84:87]
	v_mfma_f32_16x16x32_bf16 v[80:83], v[152:155], v[194:197], v[80:83]
	v_mfma_f32_16x16x32_bf16 v[68:71], v[144:147], v[202:205], v[68:71]
	v_mfma_f32_16x16x32_bf16 v[64:67], v[152:155], v[202:205], v[64:67]
	v_mfma_f32_16x16x32_bf16 v[132:135], v[148:151], v[182:185], v[132:135]
	v_mfma_f32_16x16x32_bf16 v[128:131], v[156:159], v[182:185], v[128:131]
	v_mfma_f32_16x16x32_bf16 v[108:111], v[148:151], v[190:193], v[108:111]
	v_mfma_f32_16x16x32_bf16 v[104:107], v[156:159], v[190:193], v[104:107]
	s_setprio 2
	s_barrier
	v_mfma_f32_16x16x32_bf16 v[84:87], v[148:151], v[198:201], v[84:87]
	v_mfma_f32_16x16x32_bf16 v[80:83], v[156:159], v[198:201], v[80:83]
	v_mfma_f32_16x16x32_bf16 v[68:71], v[148:151], v[218:221], v[68:71]
	v_mfma_f32_16x16x32_bf16 v[64:67], v[156:159], v[218:221], v[64:67]
	s_setprio 0
	s_add_i32 s50, s79, s61
	v_lshl_add_u64 v[206:207], v[206:207], 0, s[36:37]
	s_mov_b32 m0, s50
	ds_read_b128 v[178:181], v211 offset:49152
	ds_read_b128 v[182:185], v211 offset:50176
	ds_read_b128 v[186:189], v211 offset:51200
	ds_read_b128 v[190:193], v211 offset:52224
	ds_read_b128 v[194:197], v211 offset:53248
	ds_read_b128 v[198:201], v211 offset:54272
	ds_read_b128 v[202:205], v211 offset:55296
	ds_read_b128 v[218:221], v211 offset:56320
	global_load_lds_dwordx4 v[206:207], off
	s_add_i32 m0, s50, 0x2000
	s_add_u32 s8, s8, 0x40080
	v_lshl_add_u64 v[206:207], v[222:223], 0, s[36:37]
	s_addc_u32 s9, s9, 0
	s_add_i32 s50, s80, s61
	global_load_lds_dwordx4 v[206:207], off
	v_lshl_add_u64 v[206:207], s[8:9], 0, v[162:163]
	s_mov_b32 m0, s50
	s_nop 0
	global_load_lds_dwordx4 v[206:207], off
	v_lshl_add_u64 v[206:207], s[8:9], 0, v[166:167]
	s_add_i32 m0, s50, 0x2000
	s_nop 0
	global_load_lds_dwordx4 v[206:207], off
	v_lshl_add_u64 v[206:207], v[224:225], 0, s[36:37]
	s_mov_b32 m0, s68
	s_nop 0
	global_load_lds_dwordx4 v[206:207], off
	v_lshl_add_u64 v[206:207], v[226:227], 0, s[36:37]
	s_mov_b32 m0, s69
	s_nop 0
	global_load_lds_dwordx4 v[206:207], off
	s_waitcnt vmcnt(8)
	s_waitcnt lgkmcnt(0)
	s_barrier
	s_setprio 1
	s_waitcnt lgkmcnt(0)
	v_mfma_f32_16x16x32_bf16 v[60:63], v[96:99], v[178:181], v[60:63]
	v_mfma_f32_16x16x32_bf16 v[56:59], v[120:123], v[178:181], v[56:59]
	v_mfma_f32_16x16x32_bf16 v[44:47], v[96:99], v[186:189], v[44:47]
	v_mfma_f32_16x16x32_bf16 v[40:43], v[120:123], v[186:189], v[40:43]
	v_mfma_f32_16x16x32_bf16 v[28:31], v[96:99], v[194:197], v[28:31]
	v_mfma_f32_16x16x32_bf16 v[24:27], v[120:123], v[194:197], v[24:27]
	v_mfma_f32_16x16x32_bf16 v[12:15], v[96:99], v[202:205], v[12:15]
	v_mfma_f32_16x16x32_bf16 v[8:11], v[120:123], v[202:205], v[8:11]
	v_mfma_f32_16x16x32_bf16 v[60:63], v[100:103], v[182:185], v[60:63]
	v_mfma_f32_16x16x32_bf16 v[56:59], v[124:127], v[182:185], v[56:59]
	v_mfma_f32_16x16x32_bf16 v[44:47], v[100:103], v[190:193], v[44:47]
	v_mfma_f32_16x16x32_bf16 v[40:43], v[124:127], v[190:193], v[40:43]
	v_mfma_f32_16x16x32_bf16 v[28:31], v[100:103], v[198:201], v[28:31]
	v_mfma_f32_16x16x32_bf16 v[24:27], v[124:127], v[198:201], v[24:27]
	v_mfma_f32_16x16x32_bf16 v[12:15], v[100:103], v[218:221], v[12:15]
	v_mfma_f32_16x16x32_bf16 v[8:11], v[124:127], v[218:221], v[8:11]
	s_setprio 0
	s_setprio 1
	v_mfma_f32_16x16x32_bf16 v[52:55], v[144:147], v[178:181], v[52:55]
	v_mfma_f32_16x16x32_bf16 v[48:51], v[152:155], v[178:181], v[48:51]
	v_mfma_f32_16x16x32_bf16 v[36:39], v[144:147], v[186:189], v[36:39]
	v_mfma_f32_16x16x32_bf16 v[32:35], v[152:155], v[186:189], v[32:35]
	v_mfma_f32_16x16x32_bf16 v[20:23], v[144:147], v[194:197], v[20:23]
	v_mfma_f32_16x16x32_bf16 v[16:19], v[152:155], v[194:197], v[16:19]
	v_mfma_f32_16x16x32_bf16 v[4:7], v[144:147], v[202:205], v[4:7]
	v_mfma_f32_16x16x32_bf16 v[0:3], v[152:155], v[202:205], v[0:3]
	v_mfma_f32_16x16x32_bf16 v[52:55], v[148:151], v[182:185], v[52:55]
	v_mfma_f32_16x16x32_bf16 v[48:51], v[156:159], v[182:185], v[48:51]
	v_mfma_f32_16x16x32_bf16 v[36:39], v[148:151], v[190:193], v[36:39]
	v_mfma_f32_16x16x32_bf16 v[32:35], v[156:159], v[190:193], v[32:35]
	s_setprio 2
	s_barrier
	v_mfma_f32_16x16x32_bf16 v[20:23], v[148:151], v[198:201], v[20:23]
	v_mfma_f32_16x16x32_bf16 v[16:19], v[156:159], v[198:201], v[16:19]
	v_mfma_f32_16x16x32_bf16 v[4:7], v[148:151], v[218:221], v[4:7]
	v_mfma_f32_16x16x32_bf16 v[0:3], v[156:159], v[218:221], v[0:3]
	s_setprio 0
	s_add_i32 s78, s78, 2
	s_add_u32 s6, s6, 0x100
	s_addc_u32 s7, s7, 0
	s_add_u32 s56, s56, 0x100
	s_addc_u32 s57, s57, 0
	s_cmp_gt_u32 s78, 13
	s_cbranch_scc0 .LBB0_323
.LBB0_326:
	v_mbcnt_lo_u32_b32 v226, -1, 0
	v_mbcnt_hi_u32_b32 v226, -1, v226
	s_lshl_b32 s43, s54, 8
	v_and_b32_e32 v217, 15, v226
	v_or_b32_e32 v222, s65, v217
	v_add_u32_e32 v190, s43, v222
	v_ashrrev_i32_e32 v191, 31, v190
	v_add_u32_e32 v186, 0x80, v190
	v_add_u32_e32 v184, 0x90, v190
	v_add_u32_e32 v182, 0xa0, v190
	v_add_u32_e32 v178, 0xb0, v190
	v_lshl_add_u64 v[96:97], v[190:191], 2, s[22:23]
	v_ashrrev_i32_e32 v187, 31, v186
	v_ashrrev_i32_e32 v185, 31, v184
	v_ashrrev_i32_e32 v183, 31, v182
	v_ashrrev_i32_e32 v179, 31, v178
	v_lshl_add_u64 v[98:99], v[186:187], 2, s[22:23]
	v_lshl_add_u64 v[100:101], v[184:185], 2, s[22:23]
	v_lshl_add_u64 v[102:103], v[182:183], 2, s[22:23]
	v_lshl_add_u64 v[120:121], v[178:179], 2, s[22:23]
	global_load_dword v228, v[96:97], off
	global_load_dword v225, v[96:97], off offset:64
	global_load_dword v224, v[96:97], off offset:128
	global_load_dword v223, v[96:97], off offset:192
	global_load_dword v221, v[98:99], off
	global_load_dword v220, v[100:101], off
	global_load_dword v219, v[102:103], off
	global_load_dword v218, v[120:121], off
	v_ashrrev_i32_e32 v227, 4, v226
	s_cmp_lt_i32 s16, 8
	v_lshl_add_u32 v180, v227, 3, s67
	s_cselect_b64 s[8:9], -1, 0
	s_cmp_gt_i32 s16, 7
	v_ashrrev_i32_e32 v181, 31, v180
	s_cselect_b64 s[50:51], -1, 0
	v_lshl_add_u64 v[188:189], v[180:181], 2, s[24:25]
	s_and_b64 vcc, exec, s[50:51]
	s_cbranch_vccnz .LBB0_331
	s_lshl_b32 s6, s54, 15
	s_add_i32 s6, s6, s66
	s_and_b32 s6, s6, 0x7e000
	s_lshl_b32 s6, s6, 2
	v_lshl_or_b32 v168, v217, 9, s6
	v_lshl_add_u64 v[96:97], v[188:189], 0, v[168:169]
	global_load_dwordx4 v[156:159], v[96:97], off
	global_load_dwordx4 v[152:155], v[96:97], off offset:16
	v_cndmask_b32_e64 v96, 0, 1, s[8:9]
	v_cmp_ne_u32_e64 s[6:7], 1, v96
	s_andn2_b64 vcc, exec, s[8:9]
	s_cbranch_vccz .LBB0_332

.LBB0_336:
	s_cmp_eq_u64 s[38:39], 0
	s_cbranch_scc1 .Lalign_0
	s_barrier

.LBB0_787:
	s_lshl_b32 s23, s30, 8
	s_add_i32 s23, s23, s56
	v_mbcnt_lo_u32_b32 v146, -1, 0
	v_mbcnt_hi_u32_b32 v146, -1, v146
	s_lshl_b32 s30, s21, 7
	v_and_or_b32 v148, v146, 15, s23
	v_ashrrev_i32_e32 v149, 31, v148
	v_lshl_add_u64 v[144:145], v[148:149], 2, s[12:13]
	global_load_dword v167, v[144:145], off
	v_or_b32_e32 v158, 16, v148
	v_ashrrev_i32_e32 v159, 31, v158
	v_lshl_add_u64 v[144:145], v[158:159], 2, s[12:13]
	global_load_dword v159, v[144:145], off
	v_ashrrev_i32_e32 v146, 1, v146
	v_mov_b64_e32 v[144:145], s[14:15]
	s_ashr_i32 s31, s30, 31
	v_and_b32_e32 v168, -8, v146
	v_or_b32_e32 v160, 32, v148
	s_lshl_b64 s[30:31], s[30:31], 1
	v_or_b32_e32 v156, 48, v148
	v_add_u32_e32 v154, 0x80, v148
	v_add_u32_e32 v152, 0x90, v148
	v_add_u32_e32 v150, 0xa0, v148
	v_add_u32_e32 v146, 0xb0, v148
	v_ashrrev_i32_e32 v169, 31, v168
	v_mad_i64_i32 v[148:149], s[36:37], v148, s61, v[144:145]
	v_ashrrev_i32_e32 v161, 31, v160
	v_ashrrev_i32_e32 v157, 31, v156
	v_ashrrev_i32_e32 v155, 31, v154
	v_ashrrev_i32_e32 v153, 31, v152
	v_ashrrev_i32_e32 v151, 31, v150
	v_ashrrev_i32_e32 v147, 31, v146
	v_lshl_add_u64 v[170:171], v[148:149], 0, s[30:31]
	v_lshlrev_b64 v[148:149], 1, v[168:169]
	v_lshl_add_u64 v[168:169], v[160:161], 2, s[12:13]
	v_lshl_add_u64 v[172:173], v[156:157], 2, s[12:13]
	v_lshl_add_u64 v[174:175], v[154:155], 2, s[12:13]
	v_lshl_add_u64 v[176:177], v[152:153], 2, s[12:13]
	v_lshl_add_u64 v[178:179], v[150:151], 2, s[12:13]
	v_lshl_add_u64 v[180:181], v[146:147], 2, s[12:13]
	global_load_dword v153, v[168:169], off
	global_load_dword v155, v[172:173], off
	global_load_dword v157, v[174:175], off
	global_load_dword v161, v[176:177], off
	global_load_dword v151, v[178:179], off
	global_load_dword v147, v[180:181], off
	s_mov_b32 s21, s7
	v_lshl_add_u64 v[170:171], v[170:171], 0, s[20:21]
	v_lshl_add_u64 v[170:171], v[170:171], 0, v[148:149]
	s_andn2_b64 vcc, exec, s[4:5]
	s_mov_b64 s[4:5], -1
	s_cmp_eq_u64 s[18:19], 0
	s_cbranch_scc1 .Lalign_1
	s_barrier
.Lalign_1:
	s_waitcnt vmcnt(0)
	v_fmamk_f32 v167, v167, 0x3a800000, v166
	v_rsq_f32_e32 v168, v167
	v_fmamk_f32 v159, v159, 0x3a800000, v166
	v_pk_mul_f32 v[124:125], v[124:125], v[168:169] op_sel_hi:[1,0]
	v_pk_mul_f32 v[126:127], v[126:127], v[168:169] op_sel_hi:[1,0]
	v_pk_mul_f32 v[120:121], v[120:121], v[168:169] op_sel_hi:[1,0]
	v_pk_mul_f32 v[122:123], v[122:123], v[168:169] op_sel_hi:[1,0]
	v_rsq_f32_e32 v172, v159
	v_pk_mul_f32 v[116:117], v[116:117], v[168:169] op_sel_hi:[1,0]
	v_pk_mul_f32 v[118:119], v[118:119], v[168:169] op_sel_hi:[1,0]
	v_pk_mul_f32 v[112:113], v[112:113], v[168:169] op_sel_hi:[1,0]
	v_pk_mul_f32 v[114:115], v[114:115], v[168:169] op_sel_hi:[1,0]
	v_mul_f32_e32 v159, 0xbfb8aa3b, v124
	v_mul_f32_e32 v167, 0xbfb8aa3b, v125
	v_mul_f32_e32 v168, 0xbfb8aa3b, v126
	v_mul_f32_e32 v169, 0xbfb8aa3b, v127
	v_mul_f32_e32 v173, 0xbfb8aa3b, v120
	v_mul_f32_e32 v174, 0xbfb8aa3b, v121
	v_mul_f32_e32 v175, 0xbfb8aa3b, v122
	v_mul_f32_e32 v176, 0xbfb8aa3b, v123
	v_exp_f32_e32 v159, v159
	v_exp_f32_e32 v167, v167
	v_exp_f32_e32 v168, v168
	v_exp_f32_e32 v169, v169
	v_exp_f32_e32 v173, v173
	v_exp_f32_e32 v174, v174
	v_exp_f32_e32 v175, v175
	v_exp_f32_e32 v176, v176
	v_add_f32_e32 v159, 1.0, v159
	v_add_f32_e32 v167, 1.0, v167
	v_add_f32_e32 v177, 1.0, v168
	v_add_f32_e32 v178, 1.0, v169
	v_add_f32_e32 v173, 1.0, v173
	v_add_f32_e32 v179, 1.0, v174
	v_add_f32_e32 v180, 1.0, v175
	v_add_f32_e32 v181, 1.0, v176
	v_rcp_f32_e32 v168, v159
	v_rcp_f32_e32 v169, v167
	v_rcp_f32_e32 v174, v177
	v_rcp_f32_e32 v175, v178
	v_rcp_f32_e32 v176, v173
	v_rcp_f32_e32 v177, v179
	v_rcp_f32_e32 v178, v180
	v_rcp_f32_e32 v179, v181
	v_pk_mul_f32 v[124:125], v[124:125], v[168:169]
	v_pk_mul_f32 v[126:127], v[126:127], v[174:175]
	v_pk_mul_f32 v[120:121], v[120:121], v[176:177]
	v_pk_mul_f32 v[122:123], v[122:123], v[178:179]
	v_pk_mul_f32 v[116:117], v[116:117], v[124:125]
	v_pk_mul_f32 v[118:119], v[118:119], v[126:127]
	v_pk_mul_f32 v[120:121], v[112:113], v[120:121]
	v_pk_mul_f32 v[122:123], v[114:115], v[122:123]
	v_cvt_pk_bf16_f32 v112, v116, v117
	v_cvt_pk_bf16_f32 v113, v118, v119
	v_cvt_pk_bf16_f32 v114, v120, v121
	v_cvt_pk_bf16_f32 v115, v122, v123
	v_pk_mul_f32 v[108:109], v[108:109], v[172:173] op_sel_hi:[1,0]
	global_store_dwordx4 v[170:171], v[112:115], off
	v_mul_f32_e32 v116, 0xbfb8aa3b, v108
	v_pk_mul_f32 v[110:111], v[110:111], v[172:173] op_sel_hi:[1,0]
	v_mul_f32_e32 v112, 0xbfb8aa3b, v109
	v_exp_f32_e32 v116, v116
	v_exp_f32_e32 v113, v112
	v_mul_f32_e32 v114, 0xbfb8aa3b, v110
	v_mul_f32_e32 v115, 0xbfb8aa3b, v111
	v_exp_f32_e32 v114, v114
	v_exp_f32_e32 v115, v115
	v_add_f32_e32 v112, 1.0, v116
	v_add_f32_e32 v113, 1.0, v113
	v_rcp_f32_e32 v112, v112
	v_rcp_f32_e32 v113, v113
	v_add_f32_e32 v114, 1.0, v114
	v_add_f32_e32 v115, 1.0, v115
	v_rcp_f32_e32 v114, v114
	v_rcp_f32_e32 v115, v115
	v_pk_mul_f32 v[100:101], v[100:101], v[172:173] op_sel_hi:[1,0]
	v_pk_mul_f32 v[108:109], v[108:109], v[112:113]
	v_pk_mul_f32 v[104:105], v[104:105], v[172:173] op_sel_hi:[1,0]
	v_pk_mul_f32 v[100:101], v[100:101], v[108:109]
	v_pk_mul_f32 v[108:109], v[110:111], v[114:115]
	v_mul_f32_e32 v110, 0xbfb8aa3b, v104
	v_exp_f32_e32 v110, v110
	v_pk_mul_f32 v[102:103], v[102:103], v[172:173] op_sel_hi:[1,0]
	v_pk_mul_f32 v[106:107], v[106:107], v[172:173] op_sel_hi:[1,0]
	v_pk_mul_f32 v[102:103], v[102:103], v[108:109]
	v_mul_f32_e32 v108, 0xbfb8aa3b, v105
	v_exp_f32_e32 v109, v108
	v_add_f32_e32 v108, 1.0, v110
	v_mul_f32_e32 v110, 0xbfb8aa3b, v106
	v_mul_f32_e32 v111, 0xbfb8aa3b, v107
	v_exp_f32_e32 v110, v110
	v_exp_f32_e32 v111, v111
	v_add_f32_e32 v109, 1.0, v109
	v_rcp_f32_e32 v108, v108
	v_rcp_f32_e32 v109, v109
	v_add_f32_e32 v110, 1.0, v110
	v_add_f32_e32 v111, 1.0, v111
	v_rcp_f32_e32 v110, v110
	v_rcp_f32_e32 v111, v111
	v_pk_mul_f32 v[96:97], v[96:97], v[172:173] op_sel_hi:[1,0]
	v_pk_mul_f32 v[104:105], v[104:105], v[108:109]
	s_nop 0
	v_pk_mul_f32 v[104:105], v[96:97], v[104:105]
	v_pk_mul_f32 v[96:97], v[98:99], v[172:173] op_sel_hi:[1,0]
	v_pk_mul_f32 v[98:99], v[106:107], v[110:111]
	s_nop 0
	v_pk_mul_f32 v[106:107], v[96:97], v[98:99]
	v_mad_i64_i32 v[96:97], s[36:37], v158, s61, v[144:145]
	v_lshl_add_u64 v[96:97], v[96:97], 0, s[30:31]
	v_lshl_add_u64 v[96:97], v[96:97], 0, s[20:21]
	v_lshl_add_u64 v[108:109], v[96:97], 0, v[148:149]
	v_fmamk_f32 v97, v153, 0x3a800000, v166
	v_cvt_pk_bf16_f32 v96, v100, v101
	v_rsq_f32_e32 v100, v97
	v_cvt_pk_bf16_f32 v97, v102, v103
	v_cvt_pk_bf16_f32 v98, v104, v105
	v_cvt_pk_bf16_f32 v99, v106, v107
	v_pk_mul_f32 v[92:93], v[92:93], v[100:101] op_sel_hi:[1,0]
	global_store_dwordx4 v[108:109], v[96:99], off
	v_mul_f32_e32 v101, 0xbfb8aa3b, v92
	v_exp_f32_e32 v101, v101
	v_mul_f32_e32 v96, 0xbfb8aa3b, v93
	v_exp_f32_e32 v97, v96
	v_pk_mul_f32 v[94:95], v[94:95], v[100:101] op_sel_hi:[1,0]
	s_nop 0
	v_mul_f32_e32 v98, 0xbfb8aa3b, v94
	v_mul_f32_e32 v99, 0xbfb8aa3b, v95
	v_exp_f32_e32 v98, v98
	v_exp_f32_e32 v99, v99
	v_add_f32_e32 v96, 1.0, v101
	v_add_f32_e32 v97, 1.0, v97
	v_rcp_f32_e32 v96, v96
	v_rcp_f32_e32 v97, v97
	v_add_f32_e32 v98, 1.0, v98
	v_add_f32_e32 v99, 1.0, v99
	v_rcp_f32_e32 v98, v98
	v_rcp_f32_e32 v99, v99
	v_pk_mul_f32 v[84:85], v[84:85], v[100:101] op_sel_hi:[1,0]
	v_pk_mul_f32 v[92:93], v[92:93], v[96:97]
	v_pk_mul_f32 v[88:89], v[88:89], v[100:101] op_sel_hi:[1,0]
	v_pk_mul_f32 v[84:85], v[84:85], v[92:93]
	v_pk_mul_f32 v[92:93], v[94:95], v[98:99]
	v_mul_f32_e32 v94, 0xbfb8aa3b, v88
	v_exp_f32_e32 v94, v94
	v_pk_mul_f32 v[86:87], v[86:87], v[100:101] op_sel_hi:[1,0]
	v_pk_mul_f32 v[90:91], v[90:91], v[100:101] op_sel_hi:[1,0]
	v_pk_mul_f32 v[86:87], v[86:87], v[92:93]
	v_mul_f32_e32 v92, 0xbfb8aa3b, v89
	v_exp_f32_e32 v93, v92
	v_add_f32_e32 v92, 1.0, v94
	v_mul_f32_e32 v94, 0xbfb8aa3b, v90
	v_mul_f32_e32 v95, 0xbfb8aa3b, v91
	v_exp_f32_e32 v94, v94
	v_exp_f32_e32 v95, v95
	v_add_f32_e32 v93, 1.0, v93
	v_rcp_f32_e32 v92, v92
	v_rcp_f32_e32 v93, v93
	v_add_f32_e32 v94, 1.0, v94
	v_add_f32_e32 v95, 1.0, v95
	v_rcp_f32_e32 v94, v94
	v_rcp_f32_e32 v95, v95
	v_pk_mul_f32 v[80:81], v[80:81], v[100:101] op_sel_hi:[1,0]
	v_pk_mul_f32 v[88:89], v[88:89], v[92:93]
	s_nop 0
	v_pk_mul_f32 v[88:89], v[80:81], v[88:89]
	v_pk_mul_f32 v[80:81], v[82:83], v[100:101] op_sel_hi:[1,0]
	v_pk_mul_f32 v[82:83], v[90:91], v[94:95]
	s_nop 0
	v_pk_mul_f32 v[90:91], v[80:81], v[82:83]
	v_mad_i64_i32 v[80:81], s[36:37], v160, s61, v[144:145]
	v_lshl_add_u64 v[80:81], v[80:81], 0, s[30:31]
	v_lshl_add_u64 v[80:81], v[80:81], 0, s[20:21]
	v_lshl_add_u64 v[92:93], v[80:81], 0, v[148:149]
	v_fmamk_f32 v81, v155, 0x3a800000, v166
	v_cvt_pk_bf16_f32 v80, v84, v85
	v_rsq_f32_e32 v84, v81
	v_cvt_pk_bf16_f32 v81, v86, v87
	v_cvt_pk_bf16_f32 v82, v88, v89
	v_cvt_pk_bf16_f32 v83, v90, v91
	v_pk_mul_f32 v[76:77], v[76:77], v[84:85] op_sel_hi:[1,0]
	global_store_dwordx4 v[92:93], v[80:83], off
	v_mul_f32_e32 v85, 0xbfb8aa3b, v76
	v_exp_f32_e32 v85, v85
	v_mul_f32_e32 v80, 0xbfb8aa3b, v77
	v_exp_f32_e32 v81, v80
	v_pk_mul_f32 v[78:79], v[78:79], v[84:85] op_sel_hi:[1,0]
	s_nop 0
	v_mul_f32_e32 v82, 0xbfb8aa3b, v78
	v_mul_f32_e32 v83, 0xbfb8aa3b, v79
	v_exp_f32_e32 v82, v82
	v_exp_f32_e32 v83, v83
	v_add_f32_e32 v80, 1.0, v85
	v_add_f32_e32 v81, 1.0, v81
	v_rcp_f32_e32 v80, v80
	v_rcp_f32_e32 v81, v81
	v_add_f32_e32 v82, 1.0, v82
	v_add_f32_e32 v83, 1.0, v83
	v_rcp_f32_e32 v82, v82
	v_rcp_f32_e32 v83, v83
	v_pk_mul_f32 v[68:69], v[68:69], v[84:85] op_sel_hi:[1,0]
	v_pk_mul_f32 v[76:77], v[76:77], v[80:81]
	v_pk_mul_f32 v[72:73], v[72:73], v[84:85] op_sel_hi:[1,0]
	v_pk_mul_f32 v[68:69], v[68:69], v[76:77]
	v_pk_mul_f32 v[76:77], v[78:79], v[82:83]
	v_mul_f32_e32 v78, 0xbfb8aa3b, v72
	v_exp_f32_e32 v78, v78
	v_pk_mul_f32 v[70:71], v[70:71], v[84:85] op_sel_hi:[1,0]
	v_pk_mul_f32 v[74:75], v[74:75], v[84:85] op_sel_hi:[1,0]
	v_pk_mul_f32 v[70:71], v[70:71], v[76:77]
	v_mul_f32_e32 v76, 0xbfb8aa3b, v73
	v_exp_f32_e32 v77, v76
	v_add_f32_e32 v76, 1.0, v78
	v_mul_f32_e32 v78, 0xbfb8aa3b, v74
	v_mul_f32_e32 v79, 0xbfb8aa3b, v75
	v_exp_f32_e32 v78, v78
	v_exp_f32_e32 v79, v79
	v_add_f32_e32 v77, 1.0, v77
	v_rcp_f32_e32 v76, v76
	v_rcp_f32_e32 v77, v77
	v_add_f32_e32 v78, 1.0, v78
	v_add_f32_e32 v79, 1.0, v79
	v_rcp_f32_e32 v78, v78
	v_rcp_f32_e32 v79, v79
	v_pk_mul_f32 v[64:65], v[64:65], v[84:85] op_sel_hi:[1,0]
	v_pk_mul_f32 v[72:73], v[72:73], v[76:77]
	s_nop 0
	v_pk_mul_f32 v[72:73], v[64:65], v[72:73]
	v_pk_mul_f32 v[64:65], v[66:67], v[84:85] op_sel_hi:[1,0]
	v_pk_mul_f32 v[66:67], v[74:75], v[78:79]
	s_nop 0
	v_pk_mul_f32 v[74:75], v[64:65], v[66:67]
	v_mad_i64_i32 v[64:65], s[36:37], v156, s61, v[144:145]
	v_lshl_add_u64 v[64:65], v[64:65], 0, s[30:31]
	v_lshl_add_u64 v[64:65], v[64:65], 0, s[20:21]
	v_fmamk_f32 v66, v157, 0x3a800000, v166
	v_lshl_add_u64 v[76:77], v[64:65], 0, v[148:149]
	v_cvt_pk_bf16_f32 v64, v68, v69
	v_rsq_f32_e32 v68, v66
	v_cvt_pk_bf16_f32 v65, v70, v71
	v_cvt_pk_bf16_f32 v66, v72, v73
	v_cvt_pk_bf16_f32 v67, v74, v75
	v_pk_mul_f32 v[60:61], v[60:61], v[68:69] op_sel_hi:[1,0]
	global_store_dwordx4 v[76:77], v[64:67], off
	v_pk_mul_f32 v[62:63], v[62:63], v[68:69] op_sel_hi:[1,0]
	v_pk_mul_f32 v[52:53], v[52:53], v[68:69] op_sel_hi:[1,0]
	v_mul_f32_e32 v64, 0xbfb8aa3b, v60
	v_mul_f32_e32 v65, 0xbfb8aa3b, v61
	v_exp_f32_e32 v64, v64
	v_exp_f32_e32 v65, v65
	v_mul_f32_e32 v66, 0xbfb8aa3b, v62
	v_mul_f32_e32 v67, 0xbfb8aa3b, v63
	v_exp_f32_e32 v66, v66
	v_exp_f32_e32 v67, v67
	v_add_f32_e32 v64, 1.0, v64
	v_add_f32_e32 v65, 1.0, v65
	v_rcp_f32_e32 v64, v64
	v_rcp_f32_e32 v65, v65
	v_add_f32_e32 v66, 1.0, v66
	v_add_f32_e32 v67, 1.0, v67
	v_rcp_f32_e32 v66, v66
	v_rcp_f32_e32 v67, v67
	v_pk_mul_f32 v[60:61], v[60:61], v[64:65]
	v_pk_mul_f32 v[56:57], v[56:57], v[68:69] op_sel_hi:[1,0]
	v_pk_mul_f32 v[52:53], v[52:53], v[60:61]
	v_pk_mul_f32 v[60:61], v[62:63], v[66:67]
	v_mul_f32_e32 v62, 0xbfb8aa3b, v56
	v_exp_f32_e32 v62, v62
	v_pk_mul_f32 v[54:55], v[54:55], v[68:69] op_sel_hi:[1,0]
	v_pk_mul_f32 v[58:59], v[58:59], v[68:69] op_sel_hi:[1,0]
	v_pk_mul_f32 v[54:55], v[54:55], v[60:61]
	v_mul_f32_e32 v60, 0xbfb8aa3b, v57
	v_exp_f32_e32 v61, v60
	v_add_f32_e32 v60, 1.0, v62
	v_mul_f32_e32 v62, 0xbfb8aa3b, v58
	v_mul_f32_e32 v63, 0xbfb8aa3b, v59
	v_exp_f32_e32 v62, v62
	v_exp_f32_e32 v63, v63
	v_add_f32_e32 v61, 1.0, v61
	v_rcp_f32_e32 v60, v60
	v_rcp_f32_e32 v61, v61
	v_add_f32_e32 v62, 1.0, v62
	v_add_f32_e32 v63, 1.0, v63
	v_rcp_f32_e32 v62, v62
	v_rcp_f32_e32 v63, v63
	v_pk_mul_f32 v[48:49], v[48:49], v[68:69] op_sel_hi:[1,0]
	v_pk_mul_f32 v[56:57], v[56:57], v[60:61]
	s_nop 0
	v_pk_mul_f32 v[56:57], v[48:49], v[56:57]
	v_pk_mul_f32 v[48:49], v[50:51], v[68:69] op_sel_hi:[1,0]
	v_pk_mul_f32 v[50:51], v[58:59], v[62:63]
	s_nop 0
	v_pk_mul_f32 v[58:59], v[48:49], v[50:51]
	v_mad_i64_i32 v[48:49], s[36:37], v154, s61, v[144:145]
	v_lshl_add_u64 v[48:49], v[48:49], 0, s[30:31]
	v_lshl_add_u64 v[48:49], v[48:49], 0, s[20:21]
	v_lshl_add_u64 v[60:61], v[48:49], 0, v[148:149]
	v_fmamk_f32 v49, v161, 0x3a800000, v166
	v_cvt_pk_bf16_f32 v48, v52, v53
	v_rsq_f32_e32 v52, v49
	v_cvt_pk_bf16_f32 v49, v54, v55
	v_cvt_pk_bf16_f32 v50, v56, v57
	v_cvt_pk_bf16_f32 v51, v58, v59
	v_pk_mul_f32 v[44:45], v[44:45], v[52:53] op_sel_hi:[1,0]
	global_store_dwordx4 v[60:61], v[48:51], off
	v_mul_f32_e32 v53, 0xbfb8aa3b, v44
	v_exp_f32_e32 v53, v53
	v_mul_f32_e32 v48, 0xbfb8aa3b, v45
	v_exp_f32_e32 v49, v48
	v_pk_mul_f32 v[46:47], v[46:47], v[52:53] op_sel_hi:[1,0]
	s_nop 0
	v_mul_f32_e32 v50, 0xbfb8aa3b, v46
	v_mul_f32_e32 v51, 0xbfb8aa3b, v47
	v_exp_f32_e32 v50, v50
	v_exp_f32_e32 v51, v51
	v_add_f32_e32 v48, 1.0, v53
	v_add_f32_e32 v49, 1.0, v49
	v_rcp_f32_e32 v48, v48
	v_rcp_f32_e32 v49, v49
	v_add_f32_e32 v50, 1.0, v50
	v_add_f32_e32 v51, 1.0, v51
	v_rcp_f32_e32 v50, v50
	v_rcp_f32_e32 v51, v51
	v_pk_mul_f32 v[36:37], v[36:37], v[52:53] op_sel_hi:[1,0]
	v_pk_mul_f32 v[44:45], v[44:45], v[48:49]
	v_pk_mul_f32 v[40:41], v[40:41], v[52:53] op_sel_hi:[1,0]
	v_pk_mul_f32 v[36:37], v[36:37], v[44:45]
	v_pk_mul_f32 v[44:45], v[46:47], v[50:51]
	v_mul_f32_e32 v46, 0xbfb8aa3b, v40
	v_exp_f32_e32 v46, v46
	v_pk_mul_f32 v[38:39], v[38:39], v[52:53] op_sel_hi:[1,0]
	v_pk_mul_f32 v[42:43], v[42:43], v[52:53] op_sel_hi:[1,0]
	v_pk_mul_f32 v[38:39], v[38:39], v[44:45]
	v_mul_f32_e32 v44, 0xbfb8aa3b, v41
	v_exp_f32_e32 v45, v44
	v_add_f32_e32 v44, 1.0, v46
	v_mul_f32_e32 v46, 0xbfb8aa3b, v42
	v_mul_f32_e32 v47, 0xbfb8aa3b, v43
	v_exp_f32_e32 v46, v46
	v_exp_f32_e32 v47, v47
	v_add_f32_e32 v45, 1.0, v45
	v_rcp_f32_e32 v44, v44
	v_rcp_f32_e32 v45, v45
	v_add_f32_e32 v46, 1.0, v46
	v_add_f32_e32 v47, 1.0, v47
	v_rcp_f32_e32 v46, v46
	v_rcp_f32_e32 v47, v47
	v_pk_mul_f32 v[32:33], v[32:33], v[52:53] op_sel_hi:[1,0]
	v_pk_mul_f32 v[40:41], v[40:41], v[44:45]
	s_nop 0
	v_pk_mul_f32 v[40:41], v[32:33], v[40:41]
	v_pk_mul_f32 v[32:33], v[34:35], v[52:53] op_sel_hi:[1,0]
	v_pk_mul_f32 v[34:35], v[42:43], v[46:47]
	s_nop 0
	v_pk_mul_f32 v[42:43], v[32:33], v[34:35]
	v_mad_i64_i32 v[32:33], s[36:37], v152, s61, v[144:145]
	v_lshl_add_u64 v[32:33], v[32:33], 0, s[30:31]
	v_lshl_add_u64 v[32:33], v[32:33], 0, s[20:21]
	v_lshl_add_u64 v[44:45], v[32:33], 0, v[148:149]
	v_fmamk_f32 v33, v151, 0x3a800000, v166
	v_cvt_pk_bf16_f32 v32, v36, v37
	v_rsq_f32_e32 v36, v33
	v_cvt_pk_bf16_f32 v33, v38, v39
	v_cvt_pk_bf16_f32 v34, v40, v41
	v_cvt_pk_bf16_f32 v35, v42, v43
	v_pk_mul_f32 v[28:29], v[28:29], v[36:37] op_sel_hi:[1,0]
	global_store_dwordx4 v[44:45], v[32:35], off
	v_mul_f32_e32 v37, 0xbfb8aa3b, v28
	v_exp_f32_e32 v37, v37
	v_mul_f32_e32 v32, 0xbfb8aa3b, v29
	v_exp_f32_e32 v33, v32
	v_pk_mul_f32 v[30:31], v[30:31], v[36:37] op_sel_hi:[1,0]
	s_nop 0
	v_mul_f32_e32 v34, 0xbfb8aa3b, v30
	v_mul_f32_e32 v35, 0xbfb8aa3b, v31
	v_exp_f32_e32 v34, v34
	v_exp_f32_e32 v35, v35
	v_add_f32_e32 v32, 1.0, v37
	v_add_f32_e32 v33, 1.0, v33
	v_rcp_f32_e32 v32, v32
	v_rcp_f32_e32 v33, v33
	v_add_f32_e32 v34, 1.0, v34
	v_add_f32_e32 v35, 1.0, v35
	v_rcp_f32_e32 v34, v34
	v_rcp_f32_e32 v35, v35
	v_pk_mul_f32 v[20:21], v[20:21], v[36:37] op_sel_hi:[1,0]
	v_pk_mul_f32 v[28:29], v[28:29], v[32:33]
	v_pk_mul_f32 v[24:25], v[24:25], v[36:37] op_sel_hi:[1,0]
	v_pk_mul_f32 v[20:21], v[20:21], v[28:29]
	v_pk_mul_f32 v[28:29], v[30:31], v[34:35]
	v_mul_f32_e32 v30, 0xbfb8aa3b, v24
	v_exp_f32_e32 v30, v30
	v_pk_mul_f32 v[22:23], v[22:23], v[36:37] op_sel_hi:[1,0]
	v_pk_mul_f32 v[26:27], v[26:27], v[36:37] op_sel_hi:[1,0]
	v_pk_mul_f32 v[22:23], v[22:23], v[28:29]
	v_mul_f32_e32 v28, 0xbfb8aa3b, v25
	v_exp_f32_e32 v29, v28
	v_add_f32_e32 v28, 1.0, v30
	v_mul_f32_e32 v30, 0xbfb8aa3b, v26
	v_mul_f32_e32 v31, 0xbfb8aa3b, v27
	v_exp_f32_e32 v30, v30
	v_exp_f32_e32 v31, v31
	v_add_f32_e32 v29, 1.0, v29
	v_rcp_f32_e32 v28, v28
	v_rcp_f32_e32 v29, v29
	v_add_f32_e32 v30, 1.0, v30
	v_add_f32_e32 v31, 1.0, v31
	v_rcp_f32_e32 v30, v30
	v_rcp_f32_e32 v31, v31
	v_pk_mul_f32 v[16:17], v[16:17], v[36:37] op_sel_hi:[1,0]
	v_pk_mul_f32 v[24:25], v[24:25], v[28:29]
	s_nop 0
	v_pk_mul_f32 v[24:25], v[16:17], v[24:25]
	v_pk_mul_f32 v[16:17], v[18:19], v[36:37] op_sel_hi:[1,0]
	v_pk_mul_f32 v[18:19], v[26:27], v[30:31]
	s_nop 0
	v_pk_mul_f32 v[26:27], v[16:17], v[18:19]
	v_mad_i64_i32 v[16:17], s[36:37], v150, s61, v[144:145]
	v_lshl_add_u64 v[16:17], v[16:17], 0, s[30:31]
	v_lshl_add_u64 v[16:17], v[16:17], 0, s[20:21]
	v_lshl_add_u64 v[28:29], v[16:17], 0, v[148:149]
	v_fmamk_f32 v17, v147, 0x3a800000, v166
	v_cvt_pk_bf16_f32 v16, v20, v21
	v_rsq_f32_e32 v20, v17
	v_cvt_pk_bf16_f32 v17, v22, v23
	v_cvt_pk_bf16_f32 v18, v24, v25
	v_cvt_pk_bf16_f32 v19, v26, v27
	v_pk_mul_f32 v[12:13], v[12:13], v[20:21] op_sel_hi:[1,0]
	global_store_dwordx4 v[28:29], v[16:19], off
	v_mul_f32_e32 v21, 0xbfb8aa3b, v12
	v_exp_f32_e32 v21, v21
	v_mul_f32_e32 v16, 0xbfb8aa3b, v13
	v_exp_f32_e32 v17, v16
	v_pk_mul_f32 v[14:15], v[14:15], v[20:21] op_sel_hi:[1,0]
	s_nop 0
	v_mul_f32_e32 v18, 0xbfb8aa3b, v14
	v_mul_f32_e32 v19, 0xbfb8aa3b, v15
	v_exp_f32_e32 v18, v18
	v_exp_f32_e32 v19, v19
	v_add_f32_e32 v16, 1.0, v21
	v_add_f32_e32 v17, 1.0, v17
	v_rcp_f32_e32 v16, v16
	v_rcp_f32_e32 v17, v17
	v_add_f32_e32 v18, 1.0, v18
	v_add_f32_e32 v19, 1.0, v19
	v_rcp_f32_e32 v18, v18
	v_rcp_f32_e32 v19, v19
	v_pk_mul_f32 v[4:5], v[4:5], v[20:21] op_sel_hi:[1,0]
	v_pk_mul_f32 v[12:13], v[12:13], v[16:17]
	v_pk_mul_f32 v[8:9], v[8:9], v[20:21] op_sel_hi:[1,0]
	v_pk_mul_f32 v[4:5], v[4:5], v[12:13]
	v_pk_mul_f32 v[12:13], v[14:15], v[18:19]
	v_mul_f32_e32 v14, 0xbfb8aa3b, v8
	v_exp_f32_e32 v14, v14
	v_pk_mul_f32 v[6:7], v[6:7], v[20:21] op_sel_hi:[1,0]
	v_pk_mul_f32 v[10:11], v[10:11], v[20:21] op_sel_hi:[1,0]
	v_pk_mul_f32 v[6:7], v[6:7], v[12:13]
	v_mul_f32_e32 v12, 0xbfb8aa3b, v9
	v_exp_f32_e32 v13, v12
	v_add_f32_e32 v12, 1.0, v14
	v_mul_f32_e32 v14, 0xbfb8aa3b, v10
	v_mul_f32_e32 v15, 0xbfb8aa3b, v11
	v_exp_f32_e32 v14, v14
	v_exp_f32_e32 v15, v15
	v_add_f32_e32 v13, 1.0, v13
	v_rcp_f32_e32 v12, v12
	v_rcp_f32_e32 v13, v13
	v_add_f32_e32 v14, 1.0, v14
	v_add_f32_e32 v15, 1.0, v15
	v_rcp_f32_e32 v14, v14
	v_rcp_f32_e32 v15, v15
	v_pk_mul_f32 v[0:1], v[0:1], v[20:21] op_sel_hi:[1,0]
	v_pk_mul_f32 v[8:9], v[8:9], v[12:13]
	s_nop 0
	v_pk_mul_f32 v[8:9], v[0:1], v[8:9]
	v_pk_mul_f32 v[0:1], v[2:3], v[20:21] op_sel_hi:[1,0]
	v_pk_mul_f32 v[2:3], v[10:11], v[14:15]
	s_nop 0
	v_pk_mul_f32 v[10:11], v[0:1], v[2:3]
	v_mad_i64_i32 v[0:1], s[36:37], v146, s61, v[144:145]
	v_lshl_add_u64 v[0:1], v[0:1], 0, s[30:31]
	v_lshl_add_u64 v[0:1], v[0:1], 0, s[20:21]
	v_lshl_add_u64 v[12:13], v[0:1], 0, v[148:149]
	v_cvt_pk_bf16_f32 v0, v4, v5
	v_cvt_pk_bf16_f32 v1, v6, v7
	v_cvt_pk_bf16_f32 v2, v8, v9
	v_cvt_pk_bf16_f32 v3, v10, v11
	global_store_dwordx4 v[12:13], v[0:3], off
	s_cbranch_vccnz .LBB0_780
	s_andn2_b64 vcc, exec, s[8:9]
	s_cbranch_vccnz .LBB0_779
	s_barrier
	s_branch .LBB0_779

.LBB0_869:
	s_lshl_b32 s26, s61, 8
	s_add_i32 s26, s26, s48
	v_mbcnt_lo_u32_b32 v248, -1, 0
	v_mbcnt_hi_u32_b32 v248, -1, v248
	s_nop 0
	v_and_or_b32 v228, v248, 15, s26
	s_lshl_b32 s26, s60, 8
	s_ashr_i32 s27, s26, 31
	v_ashrrev_i32_e32 v120, 1, v248
	s_lshl_b64 s[28:29], s[26:27], 1
	v_and_b32_e32 v206, -8, v120
	s_add_u32 s28, s54, s28
	v_ashrrev_i32_e32 v207, 31, v206
	s_addc_u32 s29, s55, s29
	v_ashrrev_i32_e32 v229, 31, v228
	v_lshl_add_u64 v[120:121], v[206:207], 1, s[28:29]
	v_lshlrev_b64 v[244:245], 11, v[228:229]
	v_lshl_add_u64 v[122:123], v[120:121], 0, v[244:245]
	global_load_dwordx4 v[236:239], v[122:123], off
	global_load_dwordx4 v[240:243], v[122:123], off offset:256
	v_or_b32_e32 v224, 16, v228
	v_or_b32_e32 v220, 32, v228
	v_or_b32_e32 v216, 48, v228
	v_add_u32_e32 v212, 0x80, v228
	v_add_u32_e32 v208, 0x90, v228
	v_add_u32_e32 v204, 0xa0, v228
	v_add_u32_e32 v200, 0xb0, v228
	v_ashrrev_i32_e32 v225, 31, v224
	v_ashrrev_i32_e32 v221, 31, v220
	v_ashrrev_i32_e32 v217, 31, v216
	v_ashrrev_i32_e32 v213, 31, v212
	v_ashrrev_i32_e32 v209, 31, v208
	v_ashrrev_i32_e32 v205, 31, v204
	v_ashrrev_i32_e32 v201, 31, v200
	v_lshlrev_b64 v[230:231], 11, v[224:225]
	v_lshlrev_b64 v[226:227], 11, v[220:221]
	v_lshlrev_b64 v[222:223], 11, v[216:217]
	v_lshlrev_b64 v[218:219], 11, v[212:213]
	v_lshlrev_b64 v[214:215], 11, v[208:209]
	v_lshlrev_b64 v[210:211], 11, v[204:205]
	v_lshlrev_b64 v[202:203], 11, v[200:201]
	v_lshl_add_u64 v[122:123], v[120:121], 0, v[230:231]
	v_lshl_add_u64 v[124:125], v[120:121], 0, v[226:227]
	v_lshl_add_u64 v[126:127], v[120:121], 0, v[222:223]
	v_lshl_add_u64 v[136:137], v[120:121], 0, v[218:219]
	v_lshl_add_u64 v[138:139], v[120:121], 0, v[214:215]
	v_lshl_add_u64 v[246:247], v[120:121], 0, v[210:211]
	v_lshl_add_u64 v[120:121], v[120:121], 0, v[202:203]
	global_load_dwordx4 v[180:183], v[122:123], off
	global_load_dwordx4 v[176:179], v[122:123], off offset:256
	global_load_dwordx4 v[172:175], v[124:125], off
	global_load_dwordx4 v[168:171], v[124:125], off offset:256
	global_load_dwordx4 v[164:167], v[126:127], off
	global_load_dwordx4 v[160:163], v[126:127], off offset:256
	global_load_dwordx4 v[156:159], v[136:137], off
	global_load_dwordx4 v[152:155], v[136:137], off offset:256
	global_load_dwordx4 v[148:151], v[138:139], off
	global_load_dwordx4 v[144:147], v[138:139], off offset:256
	global_load_dwordx4 v[140:143], v[246:247], off
	s_nop 0
	global_load_dwordx4 v[136:139], v[246:247], off offset:256
	global_load_dwordx4 v[124:127], v[120:121], off
	s_nop 0
	global_load_dwordx4 v[120:123], v[120:121], off offset:256
	s_or_b64 s[26:27], s[26:27], s[18:19]
	v_lshl_add_u64 v[206:207], s[26:27], 0, v[206:207]
	v_lshl_add_u64 v[246:247], v[206:207], 1, s[14:15]
	v_cmp_gt_u32_e32 vcc, 16, v248
	v_lshl_add_u64 v[244:245], v[246:247], 0, v[244:245]
	s_cmp_eq_u64 s[22:23], 0
	s_cbranch_scc1 .Lalign_2
	s_barrier
.Lalign_2:
	s_waitcnt vmcnt(0)
	v_lshlrev_b32_e32 v246, 16, v236
	v_and_b32_e32 v247, 0xffff0000, v236
	v_lshlrev_b32_e32 v236, 16, v237
	v_and_b32_e32 v237, 0xffff0000, v237
	v_lshlrev_b32_e32 v248, 16, v238
	v_and_b32_e32 v249, 0xffff0000, v238
	v_lshlrev_b32_e32 v238, 16, v239
	v_and_b32_e32 v239, 0xffff0000, v239
	v_pk_add_f32 v[134:135], v[134:135], v[236:237]
	v_pk_add_f32 v[132:133], v[132:133], v[246:247]
	v_pk_add_f32 v[236:237], v[130:131], v[238:239]
	v_pk_add_f32 v[238:239], v[128:129], v[248:249]
	v_cvt_pk_bf16_f32 v128, v132, v133
	v_cvt_pk_bf16_f32 v129, v134, v135
	v_cvt_pk_bf16_f32 v130, v238, v239
	v_cvt_pk_bf16_f32 v131, v236, v237
	v_mul_f32_e32 v133, v133, v133
	v_mul_f32_e32 v135, v135, v135
	v_mul_f32_e32 v239, v239, v239
	v_mul_f32_e32 v237, v237, v237
	v_fmac_f32_e32 v133, v132, v132
	v_fmac_f32_e32 v135, v134, v134
	v_fmac_f32_e32 v239, v238, v238
	v_fmac_f32_e32 v237, v236, v236
	global_store_dwordx4 v[244:245], v[128:131], off
	v_lshlrev_b32_e32 v132, 16, v242
	v_lshlrev_b32_e32 v134, 16, v243
	v_add_f32_e32 v128, v133, v135
	v_add_f32_e32 v129, v239, v237
	v_add_f32_e32 v236, v128, v129
	v_lshlrev_b32_e32 v128, 16, v240
	v_and_b32_e32 v129, 0xffff0000, v240
	v_lshlrev_b32_e32 v130, 16, v241
	v_and_b32_e32 v131, 0xffff0000, v241
	v_and_b32_e32 v133, 0xffff0000, v242
	v_and_b32_e32 v135, 0xffff0000, v243
	v_pk_add_f32 v[116:117], v[116:117], v[128:129]
	v_pk_add_f32 v[118:119], v[118:119], v[130:131]
	v_pk_add_f32 v[128:129], v[114:115], v[134:135]
	v_pk_add_f32 v[114:115], v[112:113], v[132:133]
	v_mul_f32_e32 v113, v117, v117
	v_cvt_pk_bf16_f32 v112, v116, v117
	v_fmac_f32_e32 v113, v116, v116
	v_mul_f32_e32 v116, v119, v119
	v_fmac_f32_e32 v116, v118, v118
	v_add_f32_e32 v113, v113, v116
	v_mul_f32_e32 v116, v115, v115
	v_mul_f32_e32 v117, v129, v129
	v_fmac_f32_e32 v116, v114, v114
	v_fmac_f32_e32 v117, v128, v128
	v_add_f32_e32 v116, v116, v117
	v_add_f32_e32 v113, v113, v116
	v_add_f32_e32 v116, v236, v113
	ds_swizzle_b32 v117, v116 offset:swizzle(SWAP,16)
	v_cvt_pk_bf16_f32 v113, v118, v119
	v_cvt_pk_bf16_f32 v114, v114, v115
	v_cvt_pk_bf16_f32 v115, v128, v129
	global_store_dwordx4 v[244:245], v[112:115], off offset:256
	s_waitcnt lgkmcnt(0)
	s_nop 0
	v_add_f32_e32 v112, v116, v117
	v_mov_b32_e32 v113, v112
	s_nop 1
	v_permlane32_swap_b32_e32 v112, v113
	s_and_saveexec_b64 s[26:27], vcc
	s_cbranch_execz .LBB0_871
	v_lshl_add_u64 v[114:115], v[228:229], 2, s[16:17]
	v_add_f32_e32 v112, v112, v113
	global_atomic_add_f32 v[114:115], v112, off

.LBB0_952:
	ds_read_b128 v[144:147], v179
	ds_read_b128 v[148:151], v179 offset:1024
	ds_read_b128 v[152:155], v179 offset:2048
	ds_read_b128 v[156:159], v179 offset:3072
	ds_read_b128 v[160:163], v180
	ds_read_b128 v[164:167], v180 offset:1024
	ds_read_b128 v[168:171], v180 offset:2048
	ds_read_b128 v[172:175], v180 offset:3072
	s_add_u32 s40, s6, 0xfffc0080
	s_addc_u32 s41, s7, -1
	s_cmp_eq_u32 s73, 12
	s_cselect_b32 s45, s27, s41
	s_cselect_b32 s44, s39, s40
	s_cselect_b32 s41, s29, s72
	s_cselect_b32 s40, s43, s71
	v_lshl_add_u64 v[176:177], s[6:7], 0, v[136:137]
	s_add_i32 m0, s54, 0xc000
	ds_read_b128 v[184:187], v181
	ds_read_b128 v[188:191], v181 offset:1024
	ds_read_b128 v[192:195], v181 offset:2048
	ds_read_b128 v[196:199], v181 offset:3072
	ds_read_b128 v[200:203], v181 offset:4096
	ds_read_b128 v[204:207], v181 offset:5120
	ds_read_b128 v[208:211], v181 offset:6144
	ds_read_b128 v[212:215], v181 offset:7168
	global_load_lds_dwordx4 v[176:177], off
	v_lshl_add_u64 v[176:177], s[6:7], 0, v[138:139]
	s_add_i32 m0, s54, 0xe000
	s_nop 0
	global_load_lds_dwordx4 v[176:177], off
	s_waitcnt vmcnt(8)
	s_waitcnt lgkmcnt(0)
	s_barrier
	s_setprio 1
	s_waitcnt lgkmcnt(0)
	v_mfma_f32_16x16x32_bf16 v[124:127], v[144:147], v[184:187], v[124:127]
	v_mfma_f32_16x16x32_bf16 v[120:123], v[152:155], v[184:187], v[120:123]
	v_mfma_f32_16x16x32_bf16 v[108:111], v[144:147], v[192:195], v[108:111]
	v_mfma_f32_16x16x32_bf16 v[104:107], v[152:155], v[192:195], v[104:107]
	v_mfma_f32_16x16x32_bf16 v[92:95], v[144:147], v[200:203], v[92:95]
	v_mfma_f32_16x16x32_bf16 v[88:91], v[152:155], v[200:203], v[88:91]
	v_mfma_f32_16x16x32_bf16 v[76:79], v[144:147], v[208:211], v[76:79]
	v_mfma_f32_16x16x32_bf16 v[72:75], v[152:155], v[208:211], v[72:75]
	v_mfma_f32_16x16x32_bf16 v[124:127], v[148:151], v[188:191], v[124:127]
	v_mfma_f32_16x16x32_bf16 v[120:123], v[156:159], v[188:191], v[120:123]
	v_mfma_f32_16x16x32_bf16 v[108:111], v[148:151], v[196:199], v[108:111]
	v_mfma_f32_16x16x32_bf16 v[104:107], v[156:159], v[196:199], v[104:107]
	v_mfma_f32_16x16x32_bf16 v[92:95], v[148:151], v[204:207], v[92:95]
	v_mfma_f32_16x16x32_bf16 v[88:91], v[156:159], v[204:207], v[88:91]
	v_mfma_f32_16x16x32_bf16 v[76:79], v[148:151], v[212:215], v[76:79]
	v_mfma_f32_16x16x32_bf16 v[72:75], v[156:159], v[212:215], v[72:75]
	s_setprio 0
	s_setprio 1
	v_mfma_f32_16x16x32_bf16 v[116:119], v[160:163], v[184:187], v[116:119]
	v_mfma_f32_16x16x32_bf16 v[112:115], v[168:171], v[184:187], v[112:115]
	v_mfma_f32_16x16x32_bf16 v[100:103], v[160:163], v[192:195], v[100:103]
	v_mfma_f32_16x16x32_bf16 v[96:99], v[168:171], v[192:195], v[96:99]
	v_mfma_f32_16x16x32_bf16 v[84:87], v[160:163], v[200:203], v[84:87]
	v_mfma_f32_16x16x32_bf16 v[80:83], v[168:171], v[200:203], v[80:83]
	v_mfma_f32_16x16x32_bf16 v[68:71], v[160:163], v[208:211], v[68:71]
	v_mfma_f32_16x16x32_bf16 v[64:67], v[168:171], v[208:211], v[64:67]
	v_mfma_f32_16x16x32_bf16 v[116:119], v[164:167], v[188:191], v[116:119]
	v_mfma_f32_16x16x32_bf16 v[112:115], v[172:175], v[188:191], v[112:115]
	v_mfma_f32_16x16x32_bf16 v[100:103], v[164:167], v[196:199], v[100:103]
	v_mfma_f32_16x16x32_bf16 v[96:99], v[172:175], v[196:199], v[96:99]
	s_setprio 2
	s_barrier
	v_mfma_f32_16x16x32_bf16 v[84:87], v[164:167], v[204:207], v[84:87]
	v_mfma_f32_16x16x32_bf16 v[80:83], v[172:175], v[204:207], v[80:83]
	v_mfma_f32_16x16x32_bf16 v[68:71], v[164:167], v[212:215], v[68:71]
	v_mfma_f32_16x16x32_bf16 v[64:67], v[172:175], v[212:215], v[64:67]
	s_setprio 0
	s_add_i32 s74, s69, s51
	v_lshl_add_u64 v[176:177], s[40:41], 0, v[130:131]
	s_mov_b32 m0, s74
	ds_read_b128 v[184:187], v181 offset:16384
	ds_read_b128 v[188:191], v181 offset:17408
	ds_read_b128 v[192:195], v181 offset:18432
	ds_read_b128 v[196:199], v181 offset:19456
	ds_read_b128 v[200:203], v181 offset:20480
	ds_read_b128 v[204:207], v181 offset:21504
	ds_read_b128 v[208:211], v181 offset:22528
	ds_read_b128 v[212:215], v181 offset:23552
	global_load_lds_dwordx4 v[176:177], off
	s_add_i32 m0, s74, 0x2000
	s_add_u32 s74, s40, 0x40000
	v_lshl_add_u64 v[216:217], s[40:41], 0, v[134:135]
	s_addc_u32 s75, s41, 0
	s_add_i32 s76, s70, s51
	global_load_lds_dwordx4 v[216:217], off
	v_lshl_add_u64 v[218:219], s[74:75], 0, v[130:131]
	s_mov_b32 m0, s76
	v_lshl_add_u64 v[220:221], s[44:45], 0, v[132:133]
	global_load_lds_dwordx4 v[218:219], off
	v_lshl_add_u64 v[218:219], s[74:75], 0, v[134:135]
	s_add_i32 m0, s76, 0x2000
	s_nop 0
	global_load_lds_dwordx4 v[218:219], off
	v_lshl_add_u64 v[218:219], s[44:45], 0, v[128:129]
	s_mov_b32 m0, s54
	s_nop 0
	global_load_lds_dwordx4 v[218:219], off
	s_mov_b32 m0, s55
	s_nop 0
	global_load_lds_dwordx4 v[220:221], off
	s_waitcnt vmcnt(8)
	s_waitcnt lgkmcnt(0)
	s_barrier
	s_setprio 1
	s_waitcnt lgkmcnt(0)
	v_mfma_f32_16x16x32_bf16 v[60:63], v[144:147], v[184:187], v[60:63]
	v_mfma_f32_16x16x32_bf16 v[56:59], v[152:155], v[184:187], v[56:59]
	v_mfma_f32_16x16x32_bf16 v[44:47], v[144:147], v[192:195], v[44:47]
	v_mfma_f32_16x16x32_bf16 v[40:43], v[152:155], v[192:195], v[40:43]
	v_mfma_f32_16x16x32_bf16 v[28:31], v[144:147], v[200:203], v[28:31]
	v_mfma_f32_16x16x32_bf16 v[24:27], v[152:155], v[200:203], v[24:27]
	v_mfma_f32_16x16x32_bf16 v[12:15], v[144:147], v[208:211], v[12:15]
	v_mfma_f32_16x16x32_bf16 v[8:11], v[152:155], v[208:211], v[8:11]
	v_mfma_f32_16x16x32_bf16 v[60:63], v[148:151], v[188:191], v[60:63]
	v_mfma_f32_16x16x32_bf16 v[56:59], v[156:159], v[188:191], v[56:59]
	v_mfma_f32_16x16x32_bf16 v[44:47], v[148:151], v[196:199], v[44:47]
	v_mfma_f32_16x16x32_bf16 v[40:43], v[156:159], v[196:199], v[40:43]
	v_mfma_f32_16x16x32_bf16 v[28:31], v[148:151], v[204:207], v[28:31]
	v_mfma_f32_16x16x32_bf16 v[24:27], v[156:159], v[204:207], v[24:27]
	v_mfma_f32_16x16x32_bf16 v[12:15], v[148:151], v[212:215], v[12:15]
	v_mfma_f32_16x16x32_bf16 v[8:11], v[156:159], v[212:215], v[8:11]
	s_setprio 0
	s_setprio 1
	v_mfma_f32_16x16x32_bf16 v[52:55], v[160:163], v[184:187], v[52:55]
	v_mfma_f32_16x16x32_bf16 v[48:51], v[168:171], v[184:187], v[48:51]
	v_mfma_f32_16x16x32_bf16 v[36:39], v[160:163], v[192:195], v[36:39]
	v_mfma_f32_16x16x32_bf16 v[32:35], v[168:171], v[192:195], v[32:35]
	v_mfma_f32_16x16x32_bf16 v[20:23], v[160:163], v[200:203], v[20:23]
	v_mfma_f32_16x16x32_bf16 v[16:19], v[168:171], v[200:203], v[16:19]
	v_mfma_f32_16x16x32_bf16 v[4:7], v[160:163], v[208:211], v[4:7]
	v_mfma_f32_16x16x32_bf16 v[0:3], v[168:171], v[208:211], v[0:3]
	v_mfma_f32_16x16x32_bf16 v[52:55], v[164:167], v[188:191], v[52:55]
	v_mfma_f32_16x16x32_bf16 v[48:51], v[172:175], v[188:191], v[48:51]
	v_mfma_f32_16x16x32_bf16 v[36:39], v[164:167], v[196:199], v[36:39]
	v_mfma_f32_16x16x32_bf16 v[32:35], v[172:175], v[196:199], v[32:35]
	s_setprio 2
	s_barrier
	v_mfma_f32_16x16x32_bf16 v[20:23], v[164:167], v[204:207], v[20:23]
	v_mfma_f32_16x16x32_bf16 v[16:19], v[172:175], v[204:207], v[16:19]
	v_mfma_f32_16x16x32_bf16 v[4:7], v[164:167], v[212:215], v[4:7]
	v_mfma_f32_16x16x32_bf16 v[0:3], v[172:175], v[212:215], v[0:3]
	s_setprio 0
	s_add_i32 s74, 0, 0x18000
	s_add_i32 s75, 0, 0x1c000
	v_add_u32_e32 v156, s74, v178
	v_add_u32_e32 v172, s75, v178
	ds_read_b128 v[144:147], v156
	ds_read_b128 v[148:151], v156 offset:1024
	ds_read_b128 v[152:155], v156 offset:2048
	ds_read_b128 v[156:159], v156 offset:3072
	ds_read_b128 v[160:163], v172
	ds_read_b128 v[164:167], v172 offset:1024
	ds_read_b128 v[168:171], v172 offset:2048
	ds_read_b128 v[172:175], v172 offset:3072
	s_add_u32 s44, s44, 0x40000
	s_addc_u32 s45, s45, 0
	s_mov_b32 m0, s56
	v_lshl_add_u64 v[222:223], s[44:45], 0, v[128:129]
	ds_read_b128 v[184:187], v181 offset:32768
	ds_read_b128 v[188:191], v181 offset:33792
	ds_read_b128 v[192:195], v181 offset:34816
	ds_read_b128 v[196:199], v181 offset:35840
	ds_read_b128 v[200:203], v181 offset:36864
	ds_read_b128 v[204:207], v181 offset:37888
	ds_read_b128 v[208:211], v181 offset:38912
	ds_read_b128 v[212:215], v181 offset:39936
	global_load_lds_dwordx4 v[222:223], off
	v_lshl_add_u64 v[222:223], s[44:45], 0, v[132:133]
	s_mov_b32 m0, s57
	s_nop 0
	global_load_lds_dwordx4 v[222:223], off
	s_waitcnt vmcnt(8)
	s_waitcnt lgkmcnt(0)
	s_barrier
	s_setprio 1
	s_waitcnt lgkmcnt(0)
	v_mfma_f32_16x16x32_bf16 v[124:127], v[144:147], v[184:187], v[124:127]
	v_mfma_f32_16x16x32_bf16 v[120:123], v[152:155], v[184:187], v[120:123]
	v_mfma_f32_16x16x32_bf16 v[108:111], v[144:147], v[192:195], v[108:111]
	v_mfma_f32_16x16x32_bf16 v[104:107], v[152:155], v[192:195], v[104:107]
	v_mfma_f32_16x16x32_bf16 v[92:95], v[144:147], v[200:203], v[92:95]
	v_mfma_f32_16x16x32_bf16 v[88:91], v[152:155], v[200:203], v[88:91]
	v_mfma_f32_16x16x32_bf16 v[76:79], v[144:147], v[208:211], v[76:79]
	v_mfma_f32_16x16x32_bf16 v[72:75], v[152:155], v[208:211], v[72:75]
	v_mfma_f32_16x16x32_bf16 v[124:127], v[148:151], v[188:191], v[124:127]
	v_mfma_f32_16x16x32_bf16 v[120:123], v[156:159], v[188:191], v[120:123]
	v_mfma_f32_16x16x32_bf16 v[108:111], v[148:151], v[196:199], v[108:111]
	v_mfma_f32_16x16x32_bf16 v[104:107], v[156:159], v[196:199], v[104:107]
	v_mfma_f32_16x16x32_bf16 v[92:95], v[148:151], v[204:207], v[92:95]
	v_mfma_f32_16x16x32_bf16 v[88:91], v[156:159], v[204:207], v[88:91]
	v_mfma_f32_16x16x32_bf16 v[76:79], v[148:151], v[212:215], v[76:79]
	v_mfma_f32_16x16x32_bf16 v[72:75], v[156:159], v[212:215], v[72:75]
	s_setprio 0
	s_setprio 1
	v_mfma_f32_16x16x32_bf16 v[116:119], v[160:163], v[184:187], v[116:119]
	v_mfma_f32_16x16x32_bf16 v[112:115], v[168:171], v[184:187], v[112:115]
	v_mfma_f32_16x16x32_bf16 v[100:103], v[160:163], v[192:195], v[100:103]
	v_mfma_f32_16x16x32_bf16 v[96:99], v[168:171], v[192:195], v[96:99]
	v_mfma_f32_16x16x32_bf16 v[84:87], v[160:163], v[200:203], v[84:87]
	v_mfma_f32_16x16x32_bf16 v[80:83], v[168:171], v[200:203], v[80:83]
	v_mfma_f32_16x16x32_bf16 v[68:71], v[160:163], v[208:211], v[68:71]
	v_mfma_f32_16x16x32_bf16 v[64:67], v[168:171], v[208:211], v[64:67]
	v_mfma_f32_16x16x32_bf16 v[116:119], v[164:167], v[188:191], v[116:119]
	v_mfma_f32_16x16x32_bf16 v[112:115], v[172:175], v[188:191], v[112:115]
	v_mfma_f32_16x16x32_bf16 v[100:103], v[164:167], v[196:199], v[100:103]
	v_mfma_f32_16x16x32_bf16 v[96:99], v[172:175], v[196:199], v[96:99]
	s_setprio 2
	s_barrier
	v_mfma_f32_16x16x32_bf16 v[84:87], v[164:167], v[204:207], v[84:87]
	v_mfma_f32_16x16x32_bf16 v[80:83], v[172:175], v[204:207], v[80:83]
	v_mfma_f32_16x16x32_bf16 v[68:71], v[164:167], v[212:215], v[68:71]
	v_mfma_f32_16x16x32_bf16 v[64:67], v[172:175], v[212:215], v[64:67]
	s_setprio 0
	s_add_i32 s44, s74, s51
	v_lshl_add_u64 v[176:177], v[176:177], 0, s[22:23]
	s_mov_b32 m0, s44
	ds_read_b128 v[184:187], v181 offset:49152
	ds_read_b128 v[188:191], v181 offset:50176
	ds_read_b128 v[192:195], v181 offset:51200
	ds_read_b128 v[196:199], v181 offset:52224
	ds_read_b128 v[200:203], v181 offset:53248
	ds_read_b128 v[204:207], v181 offset:54272
	ds_read_b128 v[208:211], v181 offset:55296
	ds_read_b128 v[212:215], v181 offset:56320
	global_load_lds_dwordx4 v[176:177], off
	s_add_i32 m0, s44, 0x2000
	s_add_u32 s40, s40, 0x40080
	v_lshl_add_u64 v[176:177], v[216:217], 0, s[22:23]
	s_addc_u32 s41, s41, 0
	s_add_i32 s44, s75, s51
	global_load_lds_dwordx4 v[176:177], off
	v_lshl_add_u64 v[176:177], s[40:41], 0, v[130:131]
	s_mov_b32 m0, s44
	s_nop 0
	global_load_lds_dwordx4 v[176:177], off
	v_lshl_add_u64 v[176:177], s[40:41], 0, v[134:135]
	s_add_i32 m0, s44, 0x2000
	s_nop 0
	global_load_lds_dwordx4 v[176:177], off
	v_lshl_add_u64 v[176:177], v[218:219], 0, s[22:23]
	s_mov_b32 m0, s64
	s_nop 0
	global_load_lds_dwordx4 v[176:177], off
	v_lshl_add_u64 v[176:177], v[220:221], 0, s[22:23]
	s_mov_b32 m0, s65
	s_nop 0
	global_load_lds_dwordx4 v[176:177], off
	s_waitcnt vmcnt(8)
	s_waitcnt lgkmcnt(0)
	s_barrier
	s_setprio 1
	s_waitcnt lgkmcnt(0)
	v_mfma_f32_16x16x32_bf16 v[60:63], v[144:147], v[184:187], v[60:63]
	v_mfma_f32_16x16x32_bf16 v[56:59], v[152:155], v[184:187], v[56:59]
	v_mfma_f32_16x16x32_bf16 v[44:47], v[144:147], v[192:195], v[44:47]
	v_mfma_f32_16x16x32_bf16 v[40:43], v[152:155], v[192:195], v[40:43]
	v_mfma_f32_16x16x32_bf16 v[28:31], v[144:147], v[200:203], v[28:31]
	v_mfma_f32_16x16x32_bf16 v[24:27], v[152:155], v[200:203], v[24:27]
	v_mfma_f32_16x16x32_bf16 v[12:15], v[144:147], v[208:211], v[12:15]
	v_mfma_f32_16x16x32_bf16 v[8:11], v[152:155], v[208:211], v[8:11]
	v_mfma_f32_16x16x32_bf16 v[60:63], v[148:151], v[188:191], v[60:63]
	v_mfma_f32_16x16x32_bf16 v[56:59], v[156:159], v[188:191], v[56:59]
	v_mfma_f32_16x16x32_bf16 v[44:47], v[148:151], v[196:199], v[44:47]
	v_mfma_f32_16x16x32_bf16 v[40:43], v[156:159], v[196:199], v[40:43]
	v_mfma_f32_16x16x32_bf16 v[28:31], v[148:151], v[204:207], v[28:31]
	v_mfma_f32_16x16x32_bf16 v[24:27], v[156:159], v[204:207], v[24:27]
	v_mfma_f32_16x16x32_bf16 v[12:15], v[148:151], v[212:215], v[12:15]
	v_mfma_f32_16x16x32_bf16 v[8:11], v[156:159], v[212:215], v[8:11]
	s_setprio 0
	s_setprio 1
	v_mfma_f32_16x16x32_bf16 v[52:55], v[160:163], v[184:187], v[52:55]
	v_mfma_f32_16x16x32_bf16 v[48:51], v[168:171], v[184:187], v[48:51]
	v_mfma_f32_16x16x32_bf16 v[36:39], v[160:163], v[192:195], v[36:39]
	v_mfma_f32_16x16x32_bf16 v[32:35], v[168:171], v[192:195], v[32:35]
	v_mfma_f32_16x16x32_bf16 v[20:23], v[160:163], v[200:203], v[20:23]
	v_mfma_f32_16x16x32_bf16 v[16:19], v[168:171], v[200:203], v[16:19]
	v_mfma_f32_16x16x32_bf16 v[4:7], v[160:163], v[208:211], v[4:7]
	v_mfma_f32_16x16x32_bf16 v[0:3], v[168:171], v[208:211], v[0:3]
	v_mfma_f32_16x16x32_bf16 v[52:55], v[164:167], v[188:191], v[52:55]
	v_mfma_f32_16x16x32_bf16 v[48:51], v[172:175], v[188:191], v[48:51]
	v_mfma_f32_16x16x32_bf16 v[36:39], v[164:167], v[196:199], v[36:39]
	v_mfma_f32_16x16x32_bf16 v[32:35], v[172:175], v[196:199], v[32:35]
	s_setprio 2
	s_barrier
	v_mfma_f32_16x16x32_bf16 v[20:23], v[164:167], v[204:207], v[20:23]
	v_mfma_f32_16x16x32_bf16 v[16:19], v[172:175], v[204:207], v[16:19]
	v_mfma_f32_16x16x32_bf16 v[4:7], v[164:167], v[212:215], v[4:7]
	v_mfma_f32_16x16x32_bf16 v[0:3], v[172:175], v[212:215], v[0:3]
	s_setprio 0
	s_add_i32 s73, s73, 2
	s_add_u32 s6, s6, 0x100
	s_addc_u32 s7, s7, 0
	s_add_u32 s71, s71, 0x100
	s_addc_u32 s72, s72, 0
	s_cmp_gt_u32 s73, 13
	s_cbranch_scc0 .LBB0_952
.LBB0_955:
	s_ashr_i32 s27, s38, 2
	s_cmp_eq_u32 s27, 2
	s_cselect_b64 vcc, -1, 0
	s_cmp_lt_u32 s38, 4
	s_cselect_b64 s[40:41], -1, 0
	v_mbcnt_lo_u32_b32 v166, -1, 0
	v_mbcnt_hi_u32_b32 v166, -1, v166
	s_and_b64 s[6:7], s[40:41], exec
	v_ashrrev_i32_e32 v144, 1, v166
	s_cselect_b32 s6, s13, s9
	s_cselect_b32 s7, s12, s8
	v_and_b32_e32 v144, -8, v144
	v_cndmask_b32_e32 v162, 1.0, v183, vcc
	v_mov_b32_e32 v148, s7
	v_mov_b32_e32 v149, s6
	v_ashrrev_i32_e32 v145, 31, v144
	s_cmp_lg_u32 s27, 1
	v_mov_b32_e32 v146, 1.0
	v_lshl_add_u64 v[164:165], v[144:145], 2, v[148:149]
	s_cselect_b64 s[44:45], -1, 0
	s_cmp_eq_u32 s27, 1
	v_mov_b32_e32 v163, v162
	v_mov_b32_e32 v148, 1.0
	v_mov_b32_e32 v149, 1.0
	v_mov_b32_e32 v150, 1.0
	v_mov_b32_e32 v151, 1.0
	v_mov_b32_e32 v147, 1.0
	v_mov_b32_e32 v152, 1.0
	v_mov_b32_e32 v153, 1.0
	v_mov_b32_e32 v154, 1.0
	v_mov_b32_e32 v155, 1.0
	v_mov_b32_e32 v156, 1.0
	v_mov_b32_e32 v157, 1.0
	v_mov_b32_e32 v158, 1.0
	v_mov_b32_e32 v159, 1.0
	v_mov_b32_e32 v160, 1.0
	v_mov_b32_e32 v161, 1.0
	s_cbranch_scc1 .Lp8g_skip
	global_load_dwordx4 v[148:151], v[164:165], off
	global_load_dwordx4 v[224:227], v[164:165], off offset:16
	global_load_dwordx4 v[228:231], v[164:165], off offset:128
	global_load_dwordx4 v[232:235], v[164:165], off offset:144
	s_waitcnt vmcnt(0)
	v_pk_mul_f32 v[150:151], v[162:163], v[150:151]
	v_pk_mul_f32 v[148:149], v[162:163], v[148:149]
	v_pk_mul_f32 v[152:153], v[162:163], v[226:227]
	v_pk_mul_f32 v[146:147], v[162:163], v[224:225]
	v_pk_mul_f32 v[158:159], v[162:163], v[230:231]
	v_pk_mul_f32 v[156:157], v[162:163], v[228:229]
	v_pk_mul_f32 v[160:161], v[162:163], v[234:235]
	v_pk_mul_f32 v[154:155], v[162:163], v[232:233]
.Lp8g_skip:
.LBB0_957:
.LBB0_959:
.LBB0_961:
.LBB0_963:
	s_lshl_b32 s6, s42, 8
	s_add_i32 s6, s6, s62
	v_and_or_b32 v176, v166, 15, s6
	v_ashrrev_i32_e32 v177, 31, v176
	v_lshl_add_u64 v[162:163], v[176:177], 2, s[18:19]
	v_or_b32_e32 v174, 16, v176
	v_or_b32_e32 v172, 32, v176
	global_load_dword v191, v[162:163], off
	v_ashrrev_i32_e32 v175, 31, v174
	v_ashrrev_i32_e32 v173, 31, v172
	v_or_b32_e32 v170, 48, v176
	v_add_u32_e32 v168, 0x80, v176
	v_add_u32_e32 v166, 0x90, v176
	v_add_u32_e32 v164, 0xa0, v176
	v_add_u32_e32 v162, 0xb0, v176
	v_lshl_add_u64 v[184:185], v[174:175], 2, s[18:19]
	v_lshl_add_u64 v[186:187], v[172:173], 2, s[18:19]
	v_ashrrev_i32_e32 v171, 31, v170
	v_ashrrev_i32_e32 v169, 31, v168
	v_ashrrev_i32_e32 v167, 31, v166
	v_ashrrev_i32_e32 v165, 31, v164
	v_ashrrev_i32_e32 v163, 31, v162
	v_lshl_add_u64 v[192:193], v[170:171], 2, s[18:19]
	v_lshl_add_u64 v[194:195], v[168:169], 2, s[18:19]
	v_lshl_add_u64 v[196:197], v[166:167], 2, s[18:19]
	v_lshl_add_u64 v[198:199], v[164:165], 2, s[18:19]
	v_lshl_add_u64 v[200:201], v[162:163], 2, s[18:19]
	global_load_dword v190, v[184:185], off
	global_load_dword v189, v[186:187], off
	global_load_dword v188, v[192:193], off
	s_nop 0
	global_load_dword v187, v[194:195], off
	global_load_dword v186, v[196:197], off
	global_load_dword v185, v[198:199], off
	global_load_dword v184, v[200:201], off
	s_and_b32 s27, s38, -4
	s_cmp_lg_u32 s27, 4
	s_cselect_b64 s[42:43], -1, 0
	s_lshl_b32 s27, s38, 8
	s_and_b32 s27, s27, 0x300
	s_mov_b64 s[6:7], -1
	s_and_b64 vcc, exec, s[42:43]
	s_or_b32 s29, s27, s66
	s_cmp_eq_u64 s[24:25], 0
	s_cbranch_scc1 .Lalign_3
	s_barrier
.Lalign_3:
	s_waitcnt vmcnt(0)
	v_fmamk_f32 v191, v191, 0x3a800000, v182
	v_rsq_f32_e32 v192, v191
	s_nop 0
	v_pk_mul_f32 v[126:127], v[126:127], v[192:193] op_sel_hi:[1,0]
	v_pk_mul_f32 v[124:125], v[124:125], v[192:193] op_sel_hi:[1,0]
	v_pk_mul_f32 v[122:123], v[122:123], v[192:193] op_sel_hi:[1,0]
	v_pk_mul_f32 v[120:121], v[120:121], v[192:193] op_sel_hi:[1,0]
	v_pk_mul_f32 v[118:119], v[118:119], v[192:193] op_sel_hi:[1,0]
	v_pk_mul_f32 v[116:117], v[116:117], v[192:193] op_sel_hi:[1,0]
	v_pk_mul_f32 v[114:115], v[114:115], v[192:193] op_sel_hi:[1,0]
	v_pk_mul_f32 v[112:113], v[112:113], v[192:193] op_sel_hi:[1,0]
	s_cbranch_vccz .LBB0_965
	v_pk_mul_f32 v[192:193], v[126:127], v[126:127]
	v_pk_mul_f32 v[194:195], v[124:125], v[124:125]
	s_and_b64 s[6:7], s[40:41], exec
	v_pk_mov_b32 v[196:197], v[194:195], v[192:193] op_sel:[1,0]
	v_mov_b32_e32 v195, v193
	v_pk_add_f32 v[192:193], v[196:197], v[194:195]
	v_pk_mul_f32 v[194:195], v[122:123], v[122:123]
	v_pk_add_f32 v[192:193], v[192:193], v[192:193] op_sel_hi:[0,1]
	v_pk_mul_f32 v[196:197], v[120:121], v[120:121]
	v_mul_f32_e32 v192, v116, v116
	v_pk_mov_b32 v[198:199], v[196:197], v[194:195] op_sel:[1,0]
	v_mov_b32_e32 v197, v195
	v_pk_add_f32 v[194:195], v[198:199], v[196:197]
	v_pk_fma_f32 v[196:197], v[116:117], v[116:117], v[192:193] op_sel_hi:[1,1,0]
	v_mul_f32_e32 v192, v118, v118
	v_pk_add_f32 v[194:195], v[194:195], v[194:195] op_sel_hi:[0,1]
	v_pk_fma_f32 v[198:199], v[118:119], v[118:119], v[192:193] op_sel_hi:[1,1,0]
	v_mul_f32_e32 v196, v112, v112
	v_mul_f32_e32 v198, v113, v113
	v_mul_f32_e32 v192, v114, v114
	v_mul_f32_e32 v194, v115, v115
	v_pk_add_f32 v[196:197], v[196:197], v[198:199]
	v_pk_add_f32 v[192:193], v[192:193], v[194:195]
	s_cselect_b32 s7, s59, s61
	v_pk_add_f32 v[192:193], v[196:197], v[192:193]
	s_cselect_b32 s6, s58, s60
	v_add_f32_e32 v191, v192, v193
	ds_swizzle_b32 v192, v191 offset:swizzle(SWAP,16)
	v_pk_mul_f32 v[194:195], v[148:149], v[124:125]
	v_pk_mul_f32 v[202:203], v[146:147], v[120:121]
	s_waitcnt lgkmcnt(0)
	v_add_f32_e32 v191, v191, v192
	v_mov_b32_e32 v192, v191
	s_nop 1
	v_permlane32_swap_b32_e32 v191, v192
	v_add_f32_e32 v191, v191, v192
	v_fmamk_f32 v191, v191, 0x3c800000, v182
	v_rsq_f32_e32 v196, v191
	v_lshlrev_b64 v[192:193], 11, v[176:177]
	v_lshl_add_u64 v[192:193], s[6:7], 0, v[192:193]
	s_lshl_b32 s6, s29, 1
	s_mov_b32 s7, s15
	v_lshl_add_u64 v[192:193], v[192:193], 0, s[6:7]
	v_lshl_add_u64 v[198:199], v[144:145], 1, v[192:193]
	v_pk_mul_f32 v[192:193], v[150:151], v[126:127]
	s_mov_b64 s[6:7], 0
	v_pk_mul_f32 v[200:201], v[192:193], v[196:197] op_sel_hi:[1,0]
	v_pk_mul_f32 v[192:193], v[194:195], v[196:197] op_sel_hi:[1,0]
	v_pk_mul_f32 v[194:195], v[152:153], v[122:123]
	v_cvt_pk_bf16_f32 v192, v192, v193
	v_pk_mul_f32 v[204:205], v[194:195], v[196:197] op_sel_hi:[1,0]
	v_pk_mul_f32 v[194:195], v[202:203], v[196:197] op_sel_hi:[1,0]
	v_cvt_pk_bf16_f32 v193, v200, v201
	v_cvt_pk_bf16_f32 v194, v194, v195
	v_cvt_pk_bf16_f32 v195, v204, v205
	global_store_dwordx4 v[198:199], v[192:195], off
	v_pk_mul_f32 v[202:203], v[154:155], v[112:113]
	s_nop 0
	v_pk_mul_f32 v[192:193], v[158:159], v[118:119]
	v_pk_mul_f32 v[194:195], v[156:157], v[116:117]
	v_pk_mul_f32 v[200:201], v[192:193], v[196:197] op_sel_hi:[1,0]
	v_pk_mul_f32 v[192:193], v[194:195], v[196:197] op_sel_hi:[1,0]
	v_pk_mul_f32 v[194:195], v[160:161], v[114:115]
	v_cvt_pk_bf16_f32 v192, v192, v193
	v_pk_mul_f32 v[204:205], v[194:195], v[196:197] op_sel_hi:[1,0]
	v_pk_mul_f32 v[194:195], v[202:203], v[196:197] op_sel_hi:[1,0]
	v_cvt_pk_bf16_f32 v193, v200, v201
	v_cvt_pk_bf16_f32 v194, v194, v195
	v_cvt_pk_bf16_f32 v195, v204, v205
	global_store_dwordx4 v[198:199], v[192:195], off offset:64

.LBB0_1149:
	s_lshl_b32 s30, s30, 8
	s_lshl_b32 s23, s36, 8
	s_ashr_i32 s31, s30, 31
	v_mbcnt_lo_u32_b32 v248, -1, 0
	v_mbcnt_hi_u32_b32 v248, -1, v248
	s_add_i32 s23, s23, s56
	v_ashrrev_i32_e32 v120, 1, v248
	s_lshl_b64 s[36:37], s[30:31], 1
	v_and_or_b32 v228, v248, 15, s23
	v_and_b32_e32 v226, -8, v120
	s_add_u32 s36, s60, s36
	v_ashrrev_i32_e32 v227, 31, v226
	s_addc_u32 s37, s61, s37
	v_ashrrev_i32_e32 v229, 31, v228
	v_lshl_add_u64 v[120:121], v[226:227], 1, s[36:37]
	v_lshlrev_b64 v[122:123], 11, v[228:229]
	v_lshl_add_u64 v[244:245], v[120:121], 0, v[122:123]
	global_load_dwordx4 v[236:239], v[244:245], off
	global_load_dwordx4 v[240:243], v[244:245], off offset:256
	v_or_b32_e32 v222, 16, v228
	v_or_b32_e32 v218, 32, v228
	v_or_b32_e32 v214, 48, v228
	v_add_u32_e32 v210, 0x80, v228
	v_add_u32_e32 v208, 0x90, v228
	v_add_u32_e32 v204, 0xa0, v228
	v_add_u32_e32 v200, 0xb0, v228
	v_ashrrev_i32_e32 v223, 31, v222
	v_ashrrev_i32_e32 v219, 31, v218
	v_ashrrev_i32_e32 v215, 31, v214
	v_ashrrev_i32_e32 v211, 31, v210
	v_ashrrev_i32_e32 v209, 31, v208
	v_ashrrev_i32_e32 v205, 31, v204
	v_ashrrev_i32_e32 v201, 31, v200
	v_lshlrev_b64 v[230:231], 11, v[222:223]
	v_lshlrev_b64 v[224:225], 11, v[218:219]
	v_lshlrev_b64 v[220:221], 11, v[214:215]
	v_lshlrev_b64 v[216:217], 11, v[210:211]
	v_lshlrev_b64 v[212:213], 11, v[208:209]
	v_lshlrev_b64 v[206:207], 11, v[204:205]
	v_lshlrev_b64 v[202:203], 11, v[200:201]
	v_lshl_add_u64 v[122:123], v[120:121], 0, v[230:231]
	v_lshl_add_u64 v[132:133], v[120:121], 0, v[224:225]
	v_lshl_add_u64 v[134:135], v[120:121], 0, v[220:221]
	v_lshl_add_u64 v[136:137], v[120:121], 0, v[216:217]
	v_lshl_add_u64 v[138:139], v[120:121], 0, v[212:213]
	v_lshl_add_u64 v[246:247], v[120:121], 0, v[206:207]
	v_lshl_add_u64 v[120:121], v[120:121], 0, v[202:203]
	global_load_dwordx4 v[180:183], v[122:123], off
	global_load_dwordx4 v[176:179], v[122:123], off offset:256
	global_load_dwordx4 v[172:175], v[132:133], off
	global_load_dwordx4 v[168:171], v[132:133], off offset:256
	global_load_dwordx4 v[164:167], v[134:135], off
	global_load_dwordx4 v[160:163], v[134:135], off offset:256
	global_load_dwordx4 v[156:159], v[136:137], off
	global_load_dwordx4 v[152:155], v[136:137], off offset:256
	global_load_dwordx4 v[148:151], v[138:139], off
	global_load_dwordx4 v[144:147], v[138:139], off offset:256
	global_load_dwordx4 v[140:143], v[246:247], off
	s_nop 0
	global_load_dwordx4 v[136:139], v[246:247], off offset:256
	global_load_dwordx4 v[132:135], v[120:121], off
	s_nop 0
	global_load_dwordx4 v[120:123], v[120:121], off offset:256
	v_cmp_gt_u32_e32 vcc, 16, v248
	s_cmp_eq_u64 s[20:21], 0
	s_cbranch_scc1 .Lalign_4
	s_barrier
.Lalign_4:
	s_waitcnt vmcnt(0)
	v_lshlrev_b32_e32 v246, 16, v236
	v_and_b32_e32 v247, 0xffff0000, v236
	v_lshlrev_b32_e32 v236, 16, v237
	v_and_b32_e32 v237, 0xffff0000, v237
	v_lshlrev_b32_e32 v248, 16, v238
	v_and_b32_e32 v249, 0xffff0000, v238
	v_lshlrev_b32_e32 v238, 16, v239
	v_and_b32_e32 v239, 0xffff0000, v239
	v_pk_add_f32 v[130:131], v[130:131], v[236:237]
	v_pk_add_f32 v[128:129], v[128:129], v[246:247]
	v_pk_add_f32 v[236:237], v[126:127], v[238:239]
	v_pk_add_f32 v[238:239], v[124:125], v[248:249]
	v_cvt_pk_bf16_f32 v124, v128, v129
	v_cvt_pk_bf16_f32 v125, v130, v131
	v_cvt_pk_bf16_f32 v126, v238, v239
	v_cvt_pk_bf16_f32 v127, v236, v237
	v_mul_f32_e32 v129, v129, v129
	v_mul_f32_e32 v131, v131, v131
	v_mul_f32_e32 v239, v239, v239
	v_mul_f32_e32 v237, v237, v237
	v_fmac_f32_e32 v129, v128, v128
	v_fmac_f32_e32 v131, v130, v130
	v_fmac_f32_e32 v239, v238, v238
	v_fmac_f32_e32 v237, v236, v236
	v_lshlrev_b32_e32 v250, 16, v240
	v_and_b32_e32 v251, 0xffff0000, v240
	global_store_dwordx4 v[244:245], v[124:127], off
	v_lshlrev_b32_e32 v240, 16, v241
	v_and_b32_e32 v241, 0xffff0000, v241
	v_add_f32_e32 v124, v129, v131
	v_add_f32_e32 v125, v239, v237
	v_add_f32_e32 v128, v124, v125
	v_lshlrev_b32_e32 v124, 16, v242
	v_and_b32_e32 v125, 0xffff0000, v242
	v_lshlrev_b32_e32 v126, 16, v243
	v_and_b32_e32 v127, 0xffff0000, v243
	v_pk_add_f32 v[116:117], v[116:117], v[250:251]
	v_pk_add_f32 v[118:119], v[118:119], v[240:241]
	v_pk_add_f32 v[126:127], v[114:115], v[126:127]
	v_pk_add_f32 v[114:115], v[112:113], v[124:125]
	v_mul_f32_e32 v113, v117, v117
	v_cvt_pk_bf16_f32 v112, v116, v117
	v_fmac_f32_e32 v113, v116, v116
	v_mul_f32_e32 v116, v119, v119
	v_fmac_f32_e32 v116, v118, v118
	v_add_f32_e32 v113, v113, v116
	v_mul_f32_e32 v116, v115, v115
	v_mul_f32_e32 v117, v127, v127
	v_fmac_f32_e32 v116, v114, v114
	v_fmac_f32_e32 v117, v126, v126
	v_add_f32_e32 v116, v116, v117
	v_add_f32_e32 v113, v113, v116
	v_add_f32_e32 v116, v128, v113
	ds_swizzle_b32 v117, v116 offset:swizzle(SWAP,16)
	v_cvt_pk_bf16_f32 v113, v118, v119
	v_cvt_pk_bf16_f32 v114, v114, v115
	v_cvt_pk_bf16_f32 v115, v126, v127
	global_store_dwordx4 v[244:245], v[112:115], off offset:256
	s_waitcnt lgkmcnt(0)
	s_nop 0
	v_add_f32_e32 v112, v116, v117
	v_mov_b32_e32 v113, v112
	s_nop 1
	v_permlane32_swap_b32_e32 v112, v113
	s_and_saveexec_b64 s[36:37], vcc
	s_cbranch_execz .LBB0_1151
	v_lshl_add_u64 v[114:115], v[228:229], 2, s[14:15]
	v_add_f32_e32 v112, v112, v113
	global_atomic_add_f32 v[114:115], v112, off

.LBB0_1313:
	s_lshl_b32 s4, s49, 8
	s_add_i32 s4, s4, s40
	v_mbcnt_lo_u32_b32 v128, -1, 0
	v_mbcnt_hi_u32_b32 v128, -1, v128
	v_cndmask_b32_e64 v162, 0, 1, s[10:11]
	v_and_or_b32 v194, v128, 15, s4
	s_lshl_b32 s4, s50, 8
	s_ashr_i32 s5, s4, 31
	v_ashrrev_i32_e32 v128, 1, v128
	s_lshl_b64 s[24:25], s[4:5], 1
	v_and_b32_e32 v160, -8, v128
	s_add_u32 s24, s43, s24
	v_add_u32_e32 v188, 0x80, v194
	v_ashrrev_i32_e32 v161, 31, v160
	s_addc_u32 s25, s44, s25
	v_ashrrev_i32_e32 v189, 31, v188
	v_lshl_add_u64 v[192:193], v[160:161], 1, s[24:25]
	v_lshlrev_b64 v[128:129], 11, v[188:189]
	v_add_u32_e32 v186, 0x90, v194
	v_lshl_add_u64 v[128:129], v[192:193], 0, v[128:129]
	v_ashrrev_i32_e32 v187, 31, v186
	global_load_dwordx4 v[156:159], v[128:129], off
	global_load_dwordx4 v[152:155], v[128:129], off offset:256
	v_lshlrev_b64 v[128:129], 11, v[186:187]
	v_add_u32_e32 v184, 0xa0, v194
	v_lshl_add_u64 v[128:129], v[192:193], 0, v[128:129]
	v_ashrrev_i32_e32 v185, 31, v184
	global_load_dwordx4 v[148:151], v[128:129], off
	global_load_dwordx4 v[144:147], v[128:129], off offset:256
	v_lshlrev_b64 v[128:129], 11, v[184:185]
	v_add_u32_e32 v180, 0xb0, v194
	v_lshl_add_u64 v[128:129], v[192:193], 0, v[128:129]
	v_ashrrev_i32_e32 v181, 31, v180
	global_load_dwordx4 v[140:143], v[128:129], off
	global_load_dwordx4 v[136:139], v[128:129], off offset:256
	v_lshlrev_b64 v[128:129], 11, v[180:181]
	v_lshl_add_u64 v[128:129], v[192:193], 0, v[128:129]
	global_load_dwordx4 v[132:135], v[128:129], off
	s_nop 0
	global_load_dwordx4 v[128:131], v[128:129], off offset:256
	s_or_b64 s[4:5], s[4:5], s[14:15]
	v_lshl_add_u64 v[160:161], s[4:5], 0, v[160:161]
	v_cmp_ne_u32_e64 s[4:5], 1, v162
	s_andn2_b64 vcc, exec, s[10:11]
	v_lshlrev_b64 v[182:183], 2, v[160:161]
	s_cbranch_vccnz .LBB0_1315
	v_ashrrev_i32_e32 v195, 31, v194
	v_lshlrev_b64 v[160:161], 11, v[194:195]
	v_or_b32_e32 v220, 16, v194
	v_lshl_add_u64 v[160:161], v[192:193], 0, v[160:161]
	v_ashrrev_i32_e32 v221, 31, v220
	global_load_dwordx4 v[200:203], v[160:161], off
	global_load_dwordx4 v[204:207], v[160:161], off offset:256
	v_lshlrev_b64 v[160:161], 11, v[220:221]
	v_lshl_add_u64 v[160:161], v[192:193], 0, v[160:161]
	v_or_b32_e32 v222, 32, v194
	global_load_dwordx4 v[208:211], v[160:161], off
	global_load_dwordx4 v[212:215], v[160:161], off offset:256
	v_ashrrev_i32_e32 v223, 31, v222
	v_lshlrev_b64 v[160:161], 11, v[222:223]
	v_lshl_add_u64 v[160:161], v[192:193], 0, v[160:161]
	global_load_dwordx4 v[216:219], v[160:161], off
	s_nop 0
	global_load_dwordx4 v[160:163], v[160:161], off offset:256
	v_or_b32_e32 v190, 48, v194
	v_ashrrev_i32_e32 v191, 31, v190
	v_lshl_add_u64 v[224:225], s[8:9], 0, v[182:183]
	v_lshlrev_b64 v[194:195], 12, v[194:195]
	v_lshlrev_b64 v[226:227], 11, v[190:191]
	v_lshl_add_u64 v[224:225], v[224:225], 0, v[194:195]
	v_lshlrev_b64 v[194:195], 12, v[220:221]
	v_lshlrev_b64 v[220:221], 12, v[222:223]
	v_lshl_add_u64 v[222:223], v[192:193], 0, v[226:227]
	v_lshl_add_u64 v[226:227], s[8:9], 0, v[194:195]
	v_lshl_add_u64 v[228:229], s[8:9], 0, v[220:221]
	global_load_dwordx4 v[192:195], v[222:223], off offset:256
	s_nop 0
	global_load_dwordx4 v[220:223], v[222:223], off
	v_lshl_add_u64 v[226:227], v[226:227], 0, v[182:183]
	s_cmp_eq_u64 s[18:19], 0
	s_cbranch_scc1 .Lalign_6
	s_barrier
.Lalign_6:
	s_waitcnt vmcnt(0)
	v_lshlrev_b32_e32 v230, 16, v202
	v_and_b32_e32 v231, 0xffff0000, v202
	v_lshlrev_b32_e32 v202, 16, v203
	v_and_b32_e32 v203, 0xffff0000, v203
	v_lshlrev_b32_e32 v232, 16, v200
	v_and_b32_e32 v233, 0xffff0000, v200
	v_lshlrev_b32_e32 v200, 16, v201
	v_and_b32_e32 v201, 0xffff0000, v201
	v_lshlrev_b32_e32 v234, 16, v206
	v_and_b32_e32 v235, 0xffff0000, v206
	v_lshlrev_b32_e32 v206, 16, v207
	v_and_b32_e32 v207, 0xffff0000, v207
	v_lshlrev_b32_e32 v236, 16, v204
	v_and_b32_e32 v237, 0xffff0000, v204
	v_lshlrev_b32_e32 v204, 16, v205
	v_and_b32_e32 v205, 0xffff0000, v205
	v_pk_add_f32 v[122:123], v[122:123], v[202:203]
	v_pk_add_f32 v[126:127], v[126:127], v[200:201]
	v_pk_add_f32 v[124:125], v[124:125], v[232:233]
	v_pk_add_f32 v[106:107], v[106:107], v[206:207]
	v_pk_add_f32 v[104:105], v[104:105], v[234:235]
	v_pk_add_f32 v[114:115], v[114:115], v[204:205]
	v_lshlrev_b32_e32 v200, 16, v210
	v_and_b32_e32 v201, 0xffff0000, v210
	v_lshlrev_b32_e32 v202, 16, v211
	v_and_b32_e32 v203, 0xffff0000, v211
	v_lshlrev_b32_e32 v204, 16, v208
	v_and_b32_e32 v205, 0xffff0000, v208
	v_lshlrev_b32_e32 v206, 16, v209
	v_and_b32_e32 v207, 0xffff0000, v209
	v_lshlrev_b32_e32 v208, 16, v214
	v_and_b32_e32 v209, 0xffff0000, v214
	v_pk_add_f32 v[120:121], v[120:121], v[230:231]
	v_pk_add_f32 v[112:113], v[112:113], v[236:237]
	v_lshlrev_b32_e32 v210, 16, v215
	v_and_b32_e32 v211, 0xffff0000, v215
	v_lshlrev_b32_e32 v214, 16, v212
	v_and_b32_e32 v215, 0xffff0000, v212
	v_lshlrev_b32_e32 v212, 16, v213
	v_and_b32_e32 v213, 0xffff0000, v213
	global_store_dwordx4 v[224:225], v[124:127], off
	global_store_dwordx4 v[224:225], v[120:123], off offset:16
	global_store_dwordx4 v[224:225], v[112:115], off offset:512
	global_store_dwordx4 v[224:225], v[104:107], off offset:528
	v_pk_add_f32 v[92:93], v[92:93], v[208:209]
	v_pk_add_f32 v[94:95], v[94:95], v[210:211]
	v_pk_add_f32 v[106:107], v[110:111], v[202:203]
	v_pk_add_f32 v[104:105], v[108:109], v[200:201]
	v_pk_add_f32 v[110:111], v[118:119], v[206:207]
	v_pk_add_f32 v[108:109], v[116:117], v[204:205]
	v_pk_add_f32 v[98:99], v[98:99], v[212:213]
	v_pk_add_f32 v[96:97], v[96:97], v[214:215]
	global_store_dwordx4 v[226:227], v[108:111], off
	global_store_dwordx4 v[226:227], v[104:107], off offset:16
	global_store_dwordx4 v[226:227], v[96:99], off offset:512
	global_store_dwordx4 v[226:227], v[92:95], off offset:528
	s_nop 0
	v_lshlrev_b32_e32 v98, 16, v216
	v_lshlrev_b32_e32 v92, 16, v218
	v_and_b32_e32 v93, 0xffff0000, v218
	v_pk_add_f32 v[92:93], v[100:101], v[92:93]
	v_and_b32_e32 v99, 0xffff0000, v216
	v_lshlrev_b32_e32 v100, 16, v217
	v_and_b32_e32 v101, 0xffff0000, v217
	v_lshl_add_u64 v[96:97], v[228:229], 0, v[182:183]
	v_lshlrev_b32_e32 v94, 16, v219
	v_and_b32_e32 v95, 0xffff0000, v219
	v_pk_add_f32 v[90:91], v[90:91], v[100:101]
	v_pk_add_f32 v[88:89], v[88:89], v[98:99]
	v_pk_add_f32 v[94:95], v[102:103], v[94:95]
	global_store_dwordx4 v[96:97], v[88:91], off
	global_store_dwordx4 v[96:97], v[92:95], off offset:16
	s_nop 0
	v_lshlrev_b32_e32 v88, 16, v162
	v_and_b32_e32 v89, 0xffff0000, v162
	v_lshlrev_b32_e32 v90, 16, v163
	v_and_b32_e32 v91, 0xffff0000, v163
	v_pk_add_f32 v[86:87], v[86:87], v[90:91]
	v_pk_add_f32 v[84:85], v[84:85], v[88:89]
	v_lshlrev_b32_e32 v88, 16, v160
	v_and_b32_e32 v89, 0xffff0000, v160
	v_lshlrev_b32_e32 v90, 16, v161
	v_and_b32_e32 v91, 0xffff0000, v161
	v_pk_add_f32 v[82:83], v[82:83], v[90:91]
	v_pk_add_f32 v[80:81], v[80:81], v[88:89]
	global_store_dwordx4 v[96:97], v[80:83], off offset:512
	global_store_dwordx4 v[96:97], v[84:87], off offset:528
	s_nop 0
	v_lshlrev_b64 v[80:81], 12, v[190:191]
	v_lshlrev_b32_e32 v82, 16, v222
	v_and_b32_e32 v83, 0xffff0000, v222
	v_lshlrev_b32_e32 v84, 16, v223
	v_and_b32_e32 v85, 0xffff0000, v223
	v_lshl_add_u64 v[80:81], s[8:9], 0, v[80:81]
	v_pk_add_f32 v[78:79], v[78:79], v[84:85]
	v_pk_add_f32 v[76:77], v[76:77], v[82:83]
	v_lshlrev_b32_e32 v82, 16, v220
	v_and_b32_e32 v83, 0xffff0000, v220
	v_lshlrev_b32_e32 v84, 16, v221
	v_and_b32_e32 v85, 0xffff0000, v221
	v_lshl_add_u64 v[80:81], v[80:81], 0, v[182:183]
	v_pk_add_f32 v[74:75], v[74:75], v[84:85]
	v_pk_add_f32 v[72:73], v[72:73], v[82:83]
	global_store_dwordx4 v[80:81], v[72:75], off
	global_store_dwordx4 v[80:81], v[76:79], off offset:16
	s_nop 0
	v_lshlrev_b32_e32 v72, 16, v194
	v_and_b32_e32 v73, 0xffff0000, v194
	v_lshlrev_b32_e32 v74, 16, v195
	v_and_b32_e32 v75, 0xffff0000, v195
	v_pk_add_f32 v[70:71], v[70:71], v[74:75]
	v_pk_add_f32 v[68:69], v[68:69], v[72:73]
	v_lshlrev_b32_e32 v72, 16, v192
	v_and_b32_e32 v73, 0xffff0000, v192
	v_lshlrev_b32_e32 v74, 16, v193
	v_and_b32_e32 v75, 0xffff0000, v193
	v_pk_add_f32 v[66:67], v[66:67], v[74:75]
	v_pk_add_f32 v[64:65], v[64:65], v[72:73]
	global_store_dwordx4 v[80:81], v[64:67], off offset:512
	global_store_dwordx4 v[80:81], v[68:71], off offset:528
